# GLU GEMM epilogue de-serialised: bias tiles loaded once, z rows prefetched one block ahead into spare VGPRs, the 16 load-wait-compute rounds no longer wait on their own loads
# speedup vs baseline: 1.0004x; 1.0004x over previous
; __device__ __forceinline__ unsigned cvt_pk_bf16(float lo, float hi) { const f32x2 v = {lo, hi}; return __builtin_bit_cast(unsigned, __builtin_convertvector(v, bf16x2_t)); }
; __device__ __forceinline__ float bf_lo(unsigned w) { return __uint_as_float(w << 16); }
; __device__ __forceinline__ float bf_hi(unsigned w) { return __uint_as_float(w & 0xffff0000u); }
; __device__ __forceinline__ float fast_sigmoid(float v) { return __builtin_amdgcn_rcpf(1.0f + __builtin_amdgcn_exp2f(-1.4426950408889634f * v)); }
; #define ssq2 ((float*)(WSPTR() + WS_SSQ2))
;     __device__ __forceinline__ void operator()(const f32x4 (&acc)[2][2][4][2], const Unit& u, int wr, int wc, int fr, int fq) const {
;     ...
;                 const int row = row0 + ai * HALF + m * 16;
;                 float ss = 0.f;
; #pragma unroll
;                 for (int bj = 0; bj < 2; ++bj) {
;                     const int c0 = u.pn * BM + bj * HALF + wc * 32 + 8 * fq;
;                     const u32x4 zw = *(const u32x4*)(z + (size_t)row * 512 + c0);
;                     const f32x4 b0 = *(const f32x4*)(bglu + c0), b1 = *(const f32x4*)(bglu + c0 + 4);
;                     const f32x4 a0 = acc[ai][bj][m][0] + b0, a1 = acc[ai][bj][m][1] + b1;
;                     float o[8];
;                     o[0] = bf_lo(zw.x) * fast_sigmoid(a0[0]); o[1] = bf_hi(zw.x) * fast_sigmoid(a0[1]);
;                     o[2] = bf_lo(zw.y) * fast_sigmoid(a0[2]); o[3] = bf_hi(zw.y) * fast_sigmoid(a0[3]);
;                     o[4] = bf_lo(zw.z) * fast_sigmoid(a1[0]); o[5] = bf_hi(zw.z) * fast_sigmoid(a1[1]);
;                     o[6] = bf_lo(zw.w) * fast_sigmoid(a1[2]); o[7] = bf_hi(zw.w) * fast_sigmoid(a1[3]);
; #pragma unroll
;                     for (int j = 0; j < 8; ++j) ss += o[j] * o[j];
;                     u32x4 w; w.x = cvt_pk_bf16(o[0], o[1]); w.y = cvt_pk_bf16(o[2], o[3]); w.z = cvt_pk_bf16(o[4], o[5]); w.w = cvt_pk_bf16(o[6], o[7]);
;                     *(u32x4*)(s + (size_t)row * 1024 + 512 + c0) = w;
;                 }
;                 ss += __shfl_xor(ss, 16); ss += __shfl_xor(ss, 32); if (fq == 0) ssq2[((size_t)u.pn * 32768 + row) * 4 + wc] = ss;
.LBB0_590:
	v_lshl_or_b32 v142, s92, 8, v148
	v_ashrrev_i32_e32 v143, 31, v142
	v_lshl_add_u64 v[140:141], v[142:143], 2, s[80:81]
	v_lshl_add_u32 v144, s19, 8, v146
	v_ashrrev_i32_e32 v145, 31, v144
	v_lshlrev_b64 v[158:159], 10, v[144:145]
	v_lshlrev_b64 v[142:143], 1, v[142:143]
	v_lshl_add_u64 v[158:159], s[76:77], 0, v[158:159]
	v_lshl_add_u64 v[178:179], v[158:159], 0, v[142:143]
	v_mov_b64_e32 v[226:227], v[178:179]
	global_load_dwordx4 v[184:187], v[140:141], off
	global_load_dwordx4 v[188:191], v[140:141], off offset:16
	global_load_dwordx4 v[192:195], v[140:141], off offset:512
	global_load_dwordx4 v[196:199], v[140:141], off offset:528
	global_load_dwordx4 v[200:203], v[226:227], off
	global_load_dwordx4 v[204:207], v[226:227], off offset:256
	s_mov_b32 s100, 0x4000
	s_mov_b32 s101, 0
	v_lshl_add_u64 v[228:229], v[226:227], 0, s[100:101]
	global_load_dwordx4 v[210:213], v[228:229], off
	global_load_dwordx4 v[214:217], v[228:229], off offset:256
	v_lshlrev_b64 v[180:181], 11, v[144:145]
	v_lshl_add_u64 v[180:181], s[78:79], 0, v[180:181]
	v_lshl_add_u64 v[180:181], v[180:181], 0, v[142:143]
	s_ashr_i32 s93, s92, 31
	s_lshl_b64 s[92:93], s[92:93], 19
	s_waitcnt vmcnt(2)
	v_mov_b32_e32 v150, v184
	v_mov_b32_e32 v151, v185
	v_mov_b32_e32 v152, v186
	v_mov_b32_e32 v153, v187
	v_mov_b32_e32 v154, v188
	v_mov_b32_e32 v155, v189
	v_mov_b32_e32 v156, v190
	v_mov_b32_e32 v157, v191
	v_mov_b32_e32 v158, v200
	v_mov_b32_e32 v159, v201
	v_mov_b32_e32 v160, v202
	v_mov_b32_e32 v161, v203
	v_pk_add_f32 v[128:129], v[128:129], v[152:153]
	v_pk_add_f32 v[126:127], v[126:127], v[150:151]
	v_pk_add_f32 v[124:125], v[124:125], v[156:157]
	v_pk_add_f32 v[122:123], v[122:123], v[154:155]
	v_mul_f32_e32 v126, 0xbfb8aa3b, v126
	v_mul_f32_e32 v127, 0xbfb8aa3b, v127
	v_mul_f32_e32 v128, 0xbfb8aa3b, v128
	v_mul_f32_e32 v129, 0xbfb8aa3b, v129
	v_mul_f32_e32 v150, 0xbfb8aa3b, v122
	v_mul_f32_e32 v151, 0xbfb8aa3b, v123
	v_mul_f32_e32 v152, 0xbfb8aa3b, v124
	v_mul_f32_e32 v153, 0xbfb8aa3b, v125
	v_exp_f32_e32 v154, v126
	v_exp_f32_e32 v155, v127
	v_exp_f32_e32 v156, v128
	v_exp_f32_e32 v157, v129
	v_exp_f32_e32 v150, v150
	v_exp_f32_e32 v151, v151
	v_exp_f32_e32 v152, v152
	v_exp_f32_e32 v153, v153
	v_lshlrev_b32_e32 v122, 16, v158
	v_and_b32_e32 v123, 0xffff0000, v158
	v_lshlrev_b32_e32 v124, 16, v159
	v_and_b32_e32 v125, 0xffff0000, v159
	v_lshlrev_b32_e32 v126, 16, v160
	v_and_b32_e32 v127, 0xffff0000, v160
	v_lshlrev_b32_e32 v128, 16, v161
	v_and_b32_e32 v129, 0xffff0000, v161
	v_add_f32_e32 v154, 1.0, v154
	v_add_f32_e32 v155, 1.0, v155
	v_add_f32_e32 v156, 1.0, v156
	v_add_f32_e32 v157, 1.0, v157
	v_add_f32_e32 v158, 1.0, v150
	v_add_f32_e32 v159, 1.0, v151
	v_add_f32_e32 v160, 1.0, v152
	v_add_f32_e32 v161, 1.0, v153
	v_rcp_f32_e32 v150, v154
	v_rcp_f32_e32 v151, v155
	v_rcp_f32_e32 v152, v156
	v_rcp_f32_e32 v153, v157
	v_rcp_f32_e32 v154, v158
	v_rcp_f32_e32 v155, v159
	v_rcp_f32_e32 v156, v160
	v_rcp_f32_e32 v157, v161
	v_pk_mul_f32 v[158:159], v[150:151], v[122:123]
	v_pk_mul_f32 v[160:161], v[152:153], v[124:125]
	v_pk_mul_f32 v[182:183], v[154:155], v[126:127]
	v_pk_mul_f32 v[128:129], v[156:157], v[128:129]
	v_cvt_pk_bf16_f32 v122, v158, v159
	v_cvt_pk_bf16_f32 v123, v160, v161
	v_cvt_pk_bf16_f32 v124, v182, v183
	v_cvt_pk_bf16_f32 v125, v128, v129
	global_store_dwordx4 v[180:181], v[122:125], off offset:1024
	s_nop 0
	v_and_b32_e32 v123, 64, v218
	v_xor_b32_e32 v122, 16, v218
	v_add_u32_e32 v123, 64, v123
	v_pk_mul_f32 v[158:159], v[158:159], v[158:159]
	v_xor_b32_e32 v178, 32, v218
	v_cmp_lt_i32_e32 vcc, v122, v123
	v_pk_mul_f32 v[160:161], v[160:161], v[160:161]
	v_add_f32_e32 v158, v158, v159
	v_cndmask_b32_e32 v122, v218, v122, vcc
	v_cmp_lt_i32_e32 vcc, v178, v123
	v_add_f32_e32 v158, v160, v158
	v_add_f32_e32 v158, v161, v158
	v_cndmask_b32_e32 v123, v218, v178, vcc
	v_pk_mul_f32 v[178:179], v[182:183], v[182:183]
	v_pk_mul_f32 v[128:129], v[128:129], v[128:129]
	v_add_f32_e32 v158, v178, v158
	v_add_f32_e32 v158, v179, v158
	v_add_f32_e32 v128, v128, v158
	v_add_f32_e32 v128, v129, v128
	v_lshlrev_b32_e32 v122, 2, v122
	v_mov_b32_e32 v124, v192
	v_mov_b32_e32 v125, v193
	v_mov_b32_e32 v126, v194
	v_mov_b32_e32 v127, v195
	v_mov_b32_e32 v150, v196
	v_mov_b32_e32 v151, v197
	v_mov_b32_e32 v152, v198
	v_mov_b32_e32 v153, v199
	v_mov_b32_e32 v154, v204
	v_mov_b32_e32 v155, v205
	v_mov_b32_e32 v156, v206
	v_mov_b32_e32 v157, v207
	v_pk_add_f32 v[118:119], v[118:119], v[124:125]
	v_pk_add_f32 v[120:121], v[120:121], v[126:127]
	v_pk_add_f32 v[114:115], v[114:115], v[150:151]
	v_mul_f32_e32 v118, 0xbfb8aa3b, v118
	v_mul_f32_e32 v119, 0xbfb8aa3b, v119
	v_pk_add_f32 v[116:117], v[116:117], v[152:153]
	v_mul_f32_e32 v120, 0xbfb8aa3b, v120
	v_mul_f32_e32 v121, 0xbfb8aa3b, v121
	v_mul_f32_e32 v114, 0xbfb8aa3b, v114
	v_mul_f32_e32 v115, 0xbfb8aa3b, v115
	v_exp_f32_e32 v118, v118
	v_exp_f32_e32 v119, v119
	v_mul_f32_e32 v116, 0xbfb8aa3b, v116
	v_mul_f32_e32 v117, 0xbfb8aa3b, v117
	v_exp_f32_e32 v120, v120
	v_exp_f32_e32 v121, v121
	v_exp_f32_e32 v114, v114
	v_exp_f32_e32 v115, v115
	v_exp_f32_e32 v116, v116
	v_exp_f32_e32 v117, v117
	v_add_f32_e32 v118, 1.0, v118
	v_add_f32_e32 v119, 1.0, v119
	v_lshlrev_b32_e32 v124, 16, v154
	v_and_b32_e32 v125, 0xffff0000, v154
	v_lshlrev_b32_e32 v126, 16, v155
	v_and_b32_e32 v127, 0xffff0000, v155
	v_add_f32_e32 v120, 1.0, v120
	v_add_f32_e32 v121, 1.0, v121
	v_add_f32_e32 v154, 1.0, v114
	v_add_f32_e32 v155, 1.0, v115
	v_rcp_f32_e32 v114, v118
	v_rcp_f32_e32 v115, v119
	v_lshlrev_b32_e32 v150, 16, v156
	v_and_b32_e32 v151, 0xffff0000, v156
	v_lshlrev_b32_e32 v152, 16, v157
	v_and_b32_e32 v153, 0xffff0000, v157
	v_add_f32_e32 v156, 1.0, v116
	v_add_f32_e32 v157, 1.0, v117
	v_rcp_f32_e32 v116, v120
	v_rcp_f32_e32 v117, v121
	v_rcp_f32_e32 v118, v154
	v_rcp_f32_e32 v119, v155
	v_pk_mul_f32 v[114:115], v[114:115], v[124:125]
	v_rcp_f32_e32 v120, v156
	v_rcp_f32_e32 v121, v157
	v_pk_mul_f32 v[124:125], v[116:117], v[126:127]
	v_pk_mul_f32 v[116:117], v[114:115], v[114:115]
	v_pk_mul_f32 v[126:127], v[118:119], v[150:151]
	v_add_f32_e32 v116, v116, v128
	v_pk_mul_f32 v[118:119], v[124:125], v[124:125]
	v_add_f32_e32 v116, v117, v116
	v_add_f32_e32 v116, v118, v116
	v_pk_mul_f32 v[150:151], v[120:121], v[152:153]
	v_pk_mul_f32 v[120:121], v[126:127], v[126:127]
	v_add_f32_e32 v116, v119, v116
	v_add_f32_e32 v116, v120, v116
	v_pk_mul_f32 v[152:153], v[150:151], v[150:151]
	v_add_f32_e32 v116, v121, v116
	v_add_f32_e32 v116, v152, v116
	v_add_f32_e32 v117, v153, v116
	ds_bpermute_b32 v119, v122, v117
	v_lshlrev_b32_e32 v116, 2, v123
	v_cvt_pk_bf16_f32 v118, v114, v115
	v_cvt_pk_bf16_f32 v120, v126, v127
	v_cvt_pk_bf16_f32 v121, v150, v151
	s_waitcnt lgkmcnt(0)
	v_add_f32_e32 v114, v117, v119
	ds_bpermute_b32 v115, v116, v114
	v_cvt_pk_bf16_f32 v119, v124, v125
	global_store_dwordx4 v[180:181], v[118:121], off offset:1280
	s_and_saveexec_b64 s[22:23], s[4:5]
	s_cbranch_execz .LBB0_592
; __device__ __forceinline__ unsigned cvt_pk_bf16(float lo, float hi) { const f32x2 v = {lo, hi}; return __builtin_bit_cast(unsigned, __builtin_convertvector(v, bf16x2_t)); }
; __device__ __forceinline__ float bf_lo(unsigned w) { return __uint_as_float(w << 16); }
; __device__ __forceinline__ float bf_hi(unsigned w) { return __uint_as_float(w & 0xffff0000u); }
; __device__ __forceinline__ float fast_sigmoid(float v) { return __builtin_amdgcn_rcpf(1.0f + __builtin_amdgcn_exp2f(-1.4426950408889634f * v)); }
; #define ssq2 ((float*)(WSPTR() + WS_SSQ2))
;     __device__ __forceinline__ void operator()(const f32x4 (&acc)[2][2][4][2], const Unit& u, int wr, int wc, int fr, int fq) const {
;     ...
;                 const int row = row0 + ai * HALF + m * 16;
;                 float ss = 0.f;
; #pragma unroll
;                 for (int bj = 0; bj < 2; ++bj) {
;                     const int c0 = u.pn * BM + bj * HALF + wc * 32 + 8 * fq;
;                     const u32x4 zw = *(const u32x4*)(z + (size_t)row * 512 + c0);
;                     const f32x4 b0 = *(const f32x4*)(bglu + c0), b1 = *(const f32x4*)(bglu + c0 + 4);
;                     const f32x4 a0 = acc[ai][bj][m][0] + b0, a1 = acc[ai][bj][m][1] + b1;
;                     float o[8];
;                     o[0] = bf_lo(zw.x) * fast_sigmoid(a0[0]); o[1] = bf_hi(zw.x) * fast_sigmoid(a0[1]);
;                     o[2] = bf_lo(zw.y) * fast_sigmoid(a0[2]); o[3] = bf_hi(zw.y) * fast_sigmoid(a0[3]);
;                     o[4] = bf_lo(zw.z) * fast_sigmoid(a1[0]); o[5] = bf_hi(zw.z) * fast_sigmoid(a1[1]);
;                     o[6] = bf_lo(zw.w) * fast_sigmoid(a1[2]); o[7] = bf_hi(zw.w) * fast_sigmoid(a1[3]);
; #pragma unroll
;                     for (int j = 0; j < 8; ++j) ss += o[j] * o[j];
;                     u32x4 w; w.x = cvt_pk_bf16(o[0], o[1]); w.y = cvt_pk_bf16(o[2], o[3]); w.z = cvt_pk_bf16(o[4], o[5]); w.w = cvt_pk_bf16(o[6], o[7]);
;                     *(u32x4*)(s + (size_t)row * 1024 + 512 + c0) = w;
;                 }
;                 ss += __shfl_xor(ss, 16); ss += __shfl_xor(ss, 32); if (fq == 0) ssq2[((size_t)u.pn * 32768 + row) * 4 + wc] = ss;
	s_add_u32 s26, s36, s92
	s_addc_u32 s27, s37, s93
	v_lshl_add_u64 v[118:119], v[144:145], 4, s[26:27]
	s_lshl_b32 s52, s38, 2
	v_lshl_add_u64 v[118:119], v[118:119], 0, s[52:53]
	s_waitcnt lgkmcnt(0)
	v_add_f32_e32 v114, v114, v115
	global_store_dword v[118:119], v114, off
.LBB0_592:
	s_or_b64 exec, exec, s[22:23]
	s_mov_b32 s100, 0x8000
	s_mov_b32 s101, 0
	v_lshl_add_u64 v[228:229], v[226:227], 0, s[100:101]
	global_load_dwordx4 v[200:203], v[228:229], off
	global_load_dwordx4 v[204:207], v[228:229], off offset:256
	s_waitcnt vmcnt(4)
	v_or_b32_e32 v114, 16, v144
	s_waitcnt lgkmcnt(0)
	v_ashrrev_i32_e32 v115, 31, v114
	v_lshlrev_b64 v[128:129], 10, v[114:115]
	v_lshl_add_u64 v[128:129], s[76:77], 0, v[128:129]
	v_lshl_add_u64 v[128:129], v[128:129], 0, v[142:143]
	v_lshlrev_b64 v[154:155], 11, v[114:115]
	v_lshl_add_u64 v[154:155], s[78:79], 0, v[154:155]
	v_lshl_add_u64 v[154:155], v[154:155], 0, v[142:143]
	v_mov_b32_e32 v118, v184
	v_mov_b32_e32 v119, v185
	v_mov_b32_e32 v120, v186
	v_mov_b32_e32 v121, v187
	v_mov_b32_e32 v124, v188
	v_mov_b32_e32 v125, v189
	v_mov_b32_e32 v126, v190
	v_mov_b32_e32 v127, v191
	v_mov_b32_e32 v150, v210
	v_mov_b32_e32 v151, v211
	v_mov_b32_e32 v152, v212
	v_mov_b32_e32 v153, v213
	v_pk_add_f32 v[112:113], v[112:113], v[120:121]
	v_pk_add_f32 v[110:111], v[110:111], v[118:119]
	v_pk_add_f32 v[108:109], v[108:109], v[126:127]
	v_pk_add_f32 v[106:107], v[106:107], v[124:125]
	v_mul_f32_e32 v110, 0xbfb8aa3b, v110
	v_mul_f32_e32 v111, 0xbfb8aa3b, v111
	v_mul_f32_e32 v112, 0xbfb8aa3b, v112
	v_mul_f32_e32 v113, 0xbfb8aa3b, v113
	v_mul_f32_e32 v106, 0xbfb8aa3b, v106
	v_mul_f32_e32 v107, 0xbfb8aa3b, v107
	v_mul_f32_e32 v108, 0xbfb8aa3b, v108
	v_mul_f32_e32 v109, 0xbfb8aa3b, v109
	v_exp_f32_e32 v117, v110
	v_exp_f32_e32 v118, v111
	v_exp_f32_e32 v119, v112
	v_exp_f32_e32 v120, v113
	v_exp_f32_e32 v121, v106
	v_exp_f32_e32 v123, v107
	v_exp_f32_e32 v124, v108
	v_exp_f32_e32 v125, v109
	v_lshlrev_b32_e32 v106, 16, v150
	v_and_b32_e32 v107, 0xffff0000, v150
	v_lshlrev_b32_e32 v108, 16, v151
	v_and_b32_e32 v109, 0xffff0000, v151
	v_lshlrev_b32_e32 v110, 16, v152
	v_and_b32_e32 v111, 0xffff0000, v152
	v_add_f32_e32 v117, 1.0, v117
	v_add_f32_e32 v126, 1.0, v118
	v_add_f32_e32 v127, 1.0, v119
	v_add_f32_e32 v145, 1.0, v120
	v_add_f32_e32 v150, 1.0, v121
	v_add_f32_e32 v123, 1.0, v123
	v_add_f32_e32 v151, 1.0, v124
	v_add_f32_e32 v152, 1.0, v125
	v_rcp_f32_e32 v118, v117
	v_rcp_f32_e32 v119, v126
	v_rcp_f32_e32 v120, v127
	v_rcp_f32_e32 v121, v145
	v_rcp_f32_e32 v124, v150
	v_rcp_f32_e32 v125, v123
	v_rcp_f32_e32 v126, v151
	v_rcp_f32_e32 v127, v152
	v_lshlrev_b32_e32 v112, 16, v153
	v_and_b32_e32 v113, 0xffff0000, v153
	v_pk_mul_f32 v[150:151], v[118:119], v[106:107]
	v_pk_mul_f32 v[152:153], v[120:121], v[108:109]
	v_pk_mul_f32 v[124:125], v[124:125], v[110:111]
	v_pk_mul_f32 v[126:127], v[126:127], v[112:113]
	v_cvt_pk_bf16_f32 v106, v150, v151
	v_cvt_pk_bf16_f32 v107, v152, v153
	v_cvt_pk_bf16_f32 v108, v124, v125
	v_cvt_pk_bf16_f32 v109, v126, v127
	global_store_dwordx4 v[154:155], v[106:109], off offset:1024
	s_nop 0
	v_pk_mul_f32 v[128:129], v[150:151], v[150:151]
	v_pk_mul_f32 v[150:151], v[152:153], v[152:153]
	v_add_f32_e32 v117, v128, v129
	v_add_f32_e32 v117, v150, v117
	v_pk_mul_f32 v[124:125], v[124:125], v[124:125]
	v_add_f32_e32 v117, v151, v117
	v_add_f32_e32 v117, v124, v117
	v_pk_mul_f32 v[126:127], v[126:127], v[126:127]
	v_add_f32_e32 v117, v125, v117
	v_add_f32_e32 v117, v126, v117
	v_add_f32_e32 v117, v127, v117
	v_mov_b32_e32 v106, v192
	v_mov_b32_e32 v107, v193
	v_mov_b32_e32 v108, v194
	v_mov_b32_e32 v109, v195
	v_mov_b32_e32 v110, v196
	v_mov_b32_e32 v111, v197
	v_mov_b32_e32 v112, v198
	v_mov_b32_e32 v113, v199
	v_mov_b32_e32 v118, v214
	v_mov_b32_e32 v119, v215
	v_mov_b32_e32 v120, v216
	v_mov_b32_e32 v121, v217
	v_pk_add_f32 v[102:103], v[102:103], v[106:107]
	v_pk_add_f32 v[104:105], v[104:105], v[108:109]
	v_pk_add_f32 v[98:99], v[98:99], v[110:111]
	v_mul_f32_e32 v102, 0xbfb8aa3b, v102
	v_mul_f32_e32 v103, 0xbfb8aa3b, v103
	v_pk_add_f32 v[100:101], v[100:101], v[112:113]
	v_mul_f32_e32 v104, 0xbfb8aa3b, v104
	v_mul_f32_e32 v105, 0xbfb8aa3b, v105
	v_mul_f32_e32 v98, 0xbfb8aa3b, v98
	v_mul_f32_e32 v99, 0xbfb8aa3b, v99
	v_exp_f32_e32 v102, v102
	v_exp_f32_e32 v103, v103
	v_mul_f32_e32 v100, 0xbfb8aa3b, v100
	v_mul_f32_e32 v101, 0xbfb8aa3b, v101
	v_exp_f32_e32 v104, v104
	v_exp_f32_e32 v105, v105
	v_exp_f32_e32 v98, v98
	v_exp_f32_e32 v99, v99
	v_exp_f32_e32 v100, v100
	v_exp_f32_e32 v101, v101
	v_add_f32_e32 v102, 1.0, v102
	v_add_f32_e32 v103, 1.0, v103
	v_lshlrev_b32_e32 v106, 16, v118
	v_and_b32_e32 v107, 0xffff0000, v118
	v_lshlrev_b32_e32 v108, 16, v119
	v_and_b32_e32 v109, 0xffff0000, v119
	v_add_f32_e32 v104, 1.0, v104
	v_add_f32_e32 v105, 1.0, v105
	v_add_f32_e32 v118, 1.0, v98
	v_add_f32_e32 v119, 1.0, v99
	v_rcp_f32_e32 v98, v102
	v_rcp_f32_e32 v99, v103
	v_lshlrev_b32_e32 v110, 16, v120
	v_and_b32_e32 v111, 0xffff0000, v120
	v_lshlrev_b32_e32 v112, 16, v121
	v_and_b32_e32 v113, 0xffff0000, v121
	v_add_f32_e32 v120, 1.0, v100
	v_add_f32_e32 v121, 1.0, v101
	v_rcp_f32_e32 v100, v104
	v_rcp_f32_e32 v101, v105
	v_rcp_f32_e32 v102, v118
	v_rcp_f32_e32 v103, v119
	v_pk_mul_f32 v[98:99], v[98:99], v[106:107]
	v_pk_mul_f32 v[106:107], v[100:101], v[108:109]
	v_pk_mul_f32 v[100:101], v[98:99], v[98:99]
	v_rcp_f32_e32 v104, v120
	v_rcp_f32_e32 v105, v121
	v_add_f32_e32 v100, v100, v117
	v_pk_mul_f32 v[108:109], v[106:107], v[106:107]
	v_add_f32_e32 v100, v101, v100
	v_pk_mul_f32 v[102:103], v[102:103], v[110:111]
	v_add_f32_e32 v100, v108, v100
	v_pk_mul_f32 v[110:111], v[102:103], v[102:103]
	v_add_f32_e32 v100, v109, v100
	v_pk_mul_f32 v[104:105], v[104:105], v[112:113]
	v_add_f32_e32 v100, v110, v100
	v_pk_mul_f32 v[112:113], v[104:105], v[104:105]
	v_add_f32_e32 v100, v111, v100
	v_add_f32_e32 v100, v112, v100
	v_add_f32_e32 v101, v113, v100
	ds_bpermute_b32 v108, v122, v101
	v_cvt_pk_bf16_f32 v100, v98, v99
	v_cvt_pk_bf16_f32 v102, v102, v103
	v_cvt_pk_bf16_f32 v103, v104, v105
	s_waitcnt lgkmcnt(0)
	v_add_f32_e32 v98, v101, v108
	ds_bpermute_b32 v99, v116, v98
	v_cvt_pk_bf16_f32 v101, v106, v107
	global_store_dwordx4 v[154:155], v[100:103], off offset:1280
	s_and_saveexec_b64 s[22:23], s[4:5]
	s_cbranch_execz .LBB0_594
	s_add_u32 s26, s36, s92
	s_addc_u32 s27, s37, s93
	v_lshl_add_u64 v[100:101], v[114:115], 4, s[26:27]
	s_lshl_b32 s52, s38, 2
	v_lshl_add_u64 v[100:101], v[100:101], 0, s[52:53]
	s_waitcnt lgkmcnt(0)
	v_add_f32_e32 v98, v98, v99
	global_store_dword v[100:101], v98, off
; __device__ __forceinline__ unsigned cvt_pk_bf16(float lo, float hi) { const f32x2 v = {lo, hi}; return __builtin_bit_cast(unsigned, __builtin_convertvector(v, bf16x2_t)); }
; __device__ __forceinline__ float bf_lo(unsigned w) { return __uint_as_float(w << 16); }
; __device__ __forceinline__ float bf_hi(unsigned w) { return __uint_as_float(w & 0xffff0000u); }
; __device__ __forceinline__ float fast_sigmoid(float v) { return __builtin_amdgcn_rcpf(1.0f + __builtin_amdgcn_exp2f(-1.4426950408889634f * v)); }
; #define ssq2 ((float*)(WSPTR() + WS_SSQ2))
;     __device__ __forceinline__ void operator()(const f32x4 (&acc)[2][2][4][2], const Unit& u, int wr, int wc, int fr, int fq) const {
;     ...
;                 const int row = row0 + ai * HALF + m * 16;
;                 float ss = 0.f;
; #pragma unroll
;                 for (int bj = 0; bj < 2; ++bj) {
;                     const int c0 = u.pn * BM + bj * HALF + wc * 32 + 8 * fq;
;                     const u32x4 zw = *(const u32x4*)(z + (size_t)row * 512 + c0);
;                     const f32x4 b0 = *(const f32x4*)(bglu + c0), b1 = *(const f32x4*)(bglu + c0 + 4);
;                     const f32x4 a0 = acc[ai][bj][m][0] + b0, a1 = acc[ai][bj][m][1] + b1;
;                     float o[8];
;                     o[0] = bf_lo(zw.x) * fast_sigmoid(a0[0]); o[1] = bf_hi(zw.x) * fast_sigmoid(a0[1]);
;                     o[2] = bf_lo(zw.y) * fast_sigmoid(a0[2]); o[3] = bf_hi(zw.y) * fast_sigmoid(a0[3]);
;                     o[4] = bf_lo(zw.z) * fast_sigmoid(a1[0]); o[5] = bf_hi(zw.z) * fast_sigmoid(a1[1]);
;                     o[6] = bf_lo(zw.w) * fast_sigmoid(a1[2]); o[7] = bf_hi(zw.w) * fast_sigmoid(a1[3]);
; #pragma unroll
;                     for (int j = 0; j < 8; ++j) ss += o[j] * o[j];
;                     u32x4 w; w.x = cvt_pk_bf16(o[0], o[1]); w.y = cvt_pk_bf16(o[2], o[3]); w.z = cvt_pk_bf16(o[4], o[5]); w.w = cvt_pk_bf16(o[6], o[7]);
;                     *(u32x4*)(s + (size_t)row * 1024 + 512 + c0) = w;
;                 }
;                 ss += __shfl_xor(ss, 16); ss += __shfl_xor(ss, 32); if (fq == 0) ssq2[((size_t)u.pn * 32768 + row) * 4 + wc] = ss;
.LBB0_594:
	s_or_b64 exec, exec, s[22:23]
	s_mov_b32 s100, 0xc000
	s_mov_b32 s101, 0
	v_lshl_add_u64 v[228:229], v[226:227], 0, s[100:101]
	global_load_dwordx4 v[210:213], v[228:229], off
	global_load_dwordx4 v[214:217], v[228:229], off offset:256
	s_waitcnt vmcnt(4)
	v_or_b32_e32 v98, 32, v144
	s_waitcnt lgkmcnt(0)
	v_ashrrev_i32_e32 v99, 31, v98
	v_lshlrev_b64 v[108:109], 10, v[98:99]
	v_lshl_add_u64 v[108:109], s[76:77], 0, v[108:109]
	v_lshl_add_u64 v[112:113], v[108:109], 0, v[142:143]
	v_lshlrev_b64 v[114:115], 11, v[98:99]
	v_lshl_add_u64 v[114:115], s[78:79], 0, v[114:115]
	v_lshl_add_u64 v[114:115], v[114:115], 0, v[142:143]
	v_mov_b32_e32 v100, v184
	v_mov_b32_e32 v101, v185
	v_mov_b32_e32 v102, v186
	v_mov_b32_e32 v103, v187
	v_mov_b32_e32 v104, v188
	v_mov_b32_e32 v105, v189
	v_mov_b32_e32 v106, v190
	v_mov_b32_e32 v107, v191
	v_mov_b32_e32 v108, v200
	v_mov_b32_e32 v109, v201
	v_mov_b32_e32 v110, v202
	v_mov_b32_e32 v111, v203
	v_pk_add_f32 v[96:97], v[96:97], v[102:103]
	v_pk_add_f32 v[94:95], v[94:95], v[100:101]
	v_pk_add_f32 v[92:93], v[92:93], v[106:107]
	v_pk_add_f32 v[90:91], v[90:91], v[104:105]
	v_mul_f32_e32 v94, 0xbfb8aa3b, v94
	v_mul_f32_e32 v95, 0xbfb8aa3b, v95
	v_mul_f32_e32 v96, 0xbfb8aa3b, v96
	v_mul_f32_e32 v97, 0xbfb8aa3b, v97
	v_mul_f32_e32 v90, 0xbfb8aa3b, v90
	v_mul_f32_e32 v91, 0xbfb8aa3b, v91
	v_mul_f32_e32 v92, 0xbfb8aa3b, v92
	v_mul_f32_e32 v93, 0xbfb8aa3b, v93
	v_exp_f32_e32 v100, v94
	v_exp_f32_e32 v101, v95
	v_exp_f32_e32 v102, v96
	v_exp_f32_e32 v103, v97
	v_exp_f32_e32 v104, v90
	v_exp_f32_e32 v105, v91
	v_exp_f32_e32 v106, v92
	v_exp_f32_e32 v107, v93
	v_add_f32_e32 v100, 1.0, v100
	v_add_f32_e32 v101, 1.0, v101
	v_add_f32_e32 v102, 1.0, v102
	v_add_f32_e32 v103, 1.0, v103
	v_add_f32_e32 v104, 1.0, v104
	v_add_f32_e32 v105, 1.0, v105
	v_add_f32_e32 v106, 1.0, v106
	v_add_f32_e32 v107, 1.0, v107
	v_rcp_f32_e32 v100, v100
	v_rcp_f32_e32 v101, v101
	v_rcp_f32_e32 v102, v102
	v_rcp_f32_e32 v103, v103
	v_rcp_f32_e32 v104, v104
	v_rcp_f32_e32 v105, v105
	v_rcp_f32_e32 v106, v106
	v_rcp_f32_e32 v107, v107
	v_lshlrev_b32_e32 v90, 16, v108
	v_and_b32_e32 v91, 0xffff0000, v108
	v_lshlrev_b32_e32 v92, 16, v109
	v_and_b32_e32 v93, 0xffff0000, v109
	v_lshlrev_b32_e32 v94, 16, v110
	v_and_b32_e32 v95, 0xffff0000, v110
	v_lshlrev_b32_e32 v96, 16, v111
	v_and_b32_e32 v97, 0xffff0000, v111
	v_pk_mul_f32 v[108:109], v[100:101], v[90:91]
	v_pk_mul_f32 v[110:111], v[102:103], v[92:93]
	v_pk_mul_f32 v[104:105], v[104:105], v[94:95]
	v_pk_mul_f32 v[106:107], v[106:107], v[96:97]
	v_cvt_pk_bf16_f32 v90, v108, v109
	v_cvt_pk_bf16_f32 v91, v110, v111
	v_cvt_pk_bf16_f32 v92, v104, v105
	v_cvt_pk_bf16_f32 v93, v106, v107
	global_store_dwordx4 v[114:115], v[90:93], off offset:1024
	s_nop 0
	v_pk_mul_f32 v[108:109], v[108:109], v[108:109]
	v_pk_mul_f32 v[110:111], v[110:111], v[110:111]
	v_add_f32_e32 v108, v108, v109
	v_add_f32_e32 v108, v110, v108
	v_pk_mul_f32 v[104:105], v[104:105], v[104:105]
	v_add_f32_e32 v108, v111, v108
	v_add_f32_e32 v104, v104, v108
	v_pk_mul_f32 v[106:107], v[106:107], v[106:107]
	v_add_f32_e32 v104, v105, v104
	v_add_f32_e32 v104, v106, v104
	v_mov_b32_e32 v90, v192
	v_mov_b32_e32 v91, v193
	v_mov_b32_e32 v92, v194
	v_mov_b32_e32 v93, v195
	v_mov_b32_e32 v94, v196
	v_mov_b32_e32 v95, v197
	v_mov_b32_e32 v96, v198
	v_mov_b32_e32 v97, v199
	v_mov_b32_e32 v100, v204
	v_mov_b32_e32 v101, v205
	v_mov_b32_e32 v102, v206
	v_mov_b32_e32 v103, v207
	v_pk_add_f32 v[86:87], v[86:87], v[90:91]
	v_pk_add_f32 v[88:89], v[88:89], v[92:93]
	v_pk_add_f32 v[82:83], v[82:83], v[94:95]
	v_mul_f32_e32 v86, 0xbfb8aa3b, v86
	v_mul_f32_e32 v87, 0xbfb8aa3b, v87
	v_pk_add_f32 v[84:85], v[84:85], v[96:97]
	v_mul_f32_e32 v88, 0xbfb8aa3b, v88
	v_mul_f32_e32 v89, 0xbfb8aa3b, v89
	v_mul_f32_e32 v82, 0xbfb8aa3b, v82
	v_mul_f32_e32 v83, 0xbfb8aa3b, v83
	v_exp_f32_e32 v86, v86
	v_exp_f32_e32 v87, v87
	v_mul_f32_e32 v84, 0xbfb8aa3b, v84
	v_mul_f32_e32 v85, 0xbfb8aa3b, v85
	v_exp_f32_e32 v88, v88
	v_exp_f32_e32 v89, v89
	v_exp_f32_e32 v82, v82
	v_exp_f32_e32 v83, v83
	v_exp_f32_e32 v84, v84
	v_exp_f32_e32 v85, v85
	v_add_f32_e32 v86, 1.0, v86
	v_add_f32_e32 v87, 1.0, v87
	v_lshlrev_b32_e32 v90, 16, v100
	v_and_b32_e32 v91, 0xffff0000, v100
	v_lshlrev_b32_e32 v92, 16, v101
	v_and_b32_e32 v93, 0xffff0000, v101
	v_add_f32_e32 v88, 1.0, v88
	v_add_f32_e32 v89, 1.0, v89
	v_add_f32_e32 v100, 1.0, v82
	v_add_f32_e32 v101, 1.0, v83
	v_rcp_f32_e32 v82, v86
	v_rcp_f32_e32 v83, v87
	v_lshlrev_b32_e32 v94, 16, v102
	v_and_b32_e32 v95, 0xffff0000, v102
	v_lshlrev_b32_e32 v96, 16, v103
	v_and_b32_e32 v97, 0xffff0000, v103
	v_add_f32_e32 v102, 1.0, v84
	v_add_f32_e32 v103, 1.0, v85
	v_rcp_f32_e32 v84, v88
	v_rcp_f32_e32 v85, v89
	v_rcp_f32_e32 v86, v100
	v_rcp_f32_e32 v87, v101
	v_pk_mul_f32 v[82:83], v[82:83], v[90:91]
	v_pk_mul_f32 v[90:91], v[84:85], v[92:93]
	v_pk_mul_f32 v[84:85], v[82:83], v[82:83]
	v_add_f32_e32 v100, v107, v104
	v_rcp_f32_e32 v88, v102
	v_rcp_f32_e32 v89, v103
	v_add_f32_e32 v84, v84, v100
	v_pk_mul_f32 v[92:93], v[90:91], v[90:91]
	v_add_f32_e32 v84, v85, v84
	v_pk_mul_f32 v[86:87], v[86:87], v[94:95]
	v_add_f32_e32 v84, v92, v84
	v_pk_mul_f32 v[94:95], v[86:87], v[86:87]
	v_add_f32_e32 v84, v93, v84
	v_pk_mul_f32 v[88:89], v[88:89], v[96:97]
	v_add_f32_e32 v84, v94, v84
	v_pk_mul_f32 v[96:97], v[88:89], v[88:89]
	v_add_f32_e32 v84, v95, v84
	v_add_f32_e32 v84, v96, v84
	v_add_f32_e32 v85, v97, v84
	ds_bpermute_b32 v92, v122, v85
	v_cvt_pk_bf16_f32 v84, v82, v83
	v_cvt_pk_bf16_f32 v86, v86, v87
	v_cvt_pk_bf16_f32 v87, v88, v89
	s_waitcnt lgkmcnt(0)
	v_add_f32_e32 v82, v85, v92
	ds_bpermute_b32 v83, v116, v82
	v_cvt_pk_bf16_f32 v85, v90, v91
	global_store_dwordx4 v[114:115], v[84:87], off offset:1280
	s_and_saveexec_b64 s[22:23], s[4:5]
	s_cbranch_execz .LBB0_596
	s_add_u32 s26, s36, s92
	s_addc_u32 s27, s37, s93
	v_lshl_add_u64 v[84:85], v[98:99], 4, s[26:27]
	s_lshl_b32 s52, s38, 2
	v_lshl_add_u64 v[84:85], v[84:85], 0, s[52:53]
	s_waitcnt lgkmcnt(0)
	v_add_f32_e32 v82, v82, v83
	global_store_dword v[84:85], v82, off
; __device__ __forceinline__ unsigned cvt_pk_bf16(float lo, float hi) { const f32x2 v = {lo, hi}; return __builtin_bit_cast(unsigned, __builtin_convertvector(v, bf16x2_t)); }
; __device__ __forceinline__ float bf_lo(unsigned w) { return __uint_as_float(w << 16); }
; __device__ __forceinline__ float bf_hi(unsigned w) { return __uint_as_float(w & 0xffff0000u); }
; __device__ __forceinline__ float fast_sigmoid(float v) { return __builtin_amdgcn_rcpf(1.0f + __builtin_amdgcn_exp2f(-1.4426950408889634f * v)); }
; #define ssq2 ((float*)(WSPTR() + WS_SSQ2))
;     __device__ __forceinline__ void operator()(const f32x4 (&acc)[2][2][4][2], const Unit& u, int wr, int wc, int fr, int fq) const {
;     ...
;         for (int ai = 0; ai < 2; ++ai)
; #pragma unroll
;             for (int m = 0; m < 4; ++m) {
;                 const int row = row0 + ai * HALF + m * 16;
;                 float ss = 0.f;
; #pragma unroll
;                 for (int bj = 0; bj < 2; ++bj) {
;                     const int c0 = u.pn * BM + bj * HALF + wc * 32 + 8 * fq;
;                     const u32x4 zw = *(const u32x4*)(z + (size_t)row * 512 + c0);
;                     const f32x4 b0 = *(const f32x4*)(bglu + c0), b1 = *(const f32x4*)(bglu + c0 + 4);
;                     const f32x4 a0 = acc[ai][bj][m][0] + b0, a1 = acc[ai][bj][m][1] + b1;
;                     float o[8];
;                     o[0] = bf_lo(zw.x) * fast_sigmoid(a0[0]); o[1] = bf_hi(zw.x) * fast_sigmoid(a0[1]);
;                     o[2] = bf_lo(zw.y) * fast_sigmoid(a0[2]); o[3] = bf_hi(zw.y) * fast_sigmoid(a0[3]);
;                     o[4] = bf_lo(zw.z) * fast_sigmoid(a1[0]); o[5] = bf_hi(zw.z) * fast_sigmoid(a1[1]);
;                     o[6] = bf_lo(zw.w) * fast_sigmoid(a1[2]); o[7] = bf_hi(zw.w) * fast_sigmoid(a1[3]);
; #pragma unroll
;                     for (int j = 0; j < 8; ++j) ss += o[j] * o[j];
;                     u32x4 w; w.x = cvt_pk_bf16(o[0], o[1]); w.y = cvt_pk_bf16(o[2], o[3]); w.z = cvt_pk_bf16(o[4], o[5]); w.w = cvt_pk_bf16(o[6], o[7]);
;                     *(u32x4*)(s + (size_t)row * 1024 + 512 + c0) = w;
;                 }
;                 ss += __shfl_xor(ss, 16); ss += __shfl_xor(ss, 32); if (fq == 0) ssq2[((size_t)u.pn * 32768 + row) * 4 + wc] = ss;
;             }
.LBB0_596:
	s_or_b64 exec, exec, s[22:23]
	s_mov_b32 s100, 0x20000
	s_mov_b32 s101, 0
	v_lshl_add_u64 v[228:229], v[226:227], 0, s[100:101]
	global_load_dwordx4 v[200:203], v[228:229], off
	global_load_dwordx4 v[204:207], v[228:229], off offset:256
	s_waitcnt vmcnt(4)
	v_or_b32_e32 v82, 48, v144
	s_waitcnt lgkmcnt(0)
	v_ashrrev_i32_e32 v83, 31, v82
	v_lshlrev_b64 v[92:93], 10, v[82:83]
	v_lshl_add_u64 v[92:93], s[76:77], 0, v[92:93]
	v_lshl_add_u64 v[96:97], v[92:93], 0, v[142:143]
	v_lshlrev_b64 v[98:99], 11, v[82:83]
	v_lshl_add_u64 v[98:99], s[78:79], 0, v[98:99]
	v_lshl_add_u64 v[98:99], v[98:99], 0, v[142:143]
	v_mov_b32_e32 v84, v184
	v_mov_b32_e32 v85, v185
	v_mov_b32_e32 v86, v186
	v_mov_b32_e32 v87, v187
	v_mov_b32_e32 v88, v188
	v_mov_b32_e32 v89, v189
	v_mov_b32_e32 v90, v190
	v_mov_b32_e32 v91, v191
	v_mov_b32_e32 v92, v210
	v_mov_b32_e32 v93, v211
	v_mov_b32_e32 v94, v212
	v_mov_b32_e32 v95, v213
	v_pk_add_f32 v[80:81], v[80:81], v[86:87]
	v_pk_add_f32 v[78:79], v[78:79], v[84:85]
	v_pk_add_f32 v[76:77], v[76:77], v[90:91]
	v_pk_add_f32 v[74:75], v[74:75], v[88:89]
	v_mul_f32_e32 v78, 0xbfb8aa3b, v78
	v_mul_f32_e32 v79, 0xbfb8aa3b, v79
	v_mul_f32_e32 v80, 0xbfb8aa3b, v80
	v_mul_f32_e32 v81, 0xbfb8aa3b, v81
	v_mul_f32_e32 v74, 0xbfb8aa3b, v74
	v_mul_f32_e32 v75, 0xbfb8aa3b, v75
	v_mul_f32_e32 v76, 0xbfb8aa3b, v76
	v_mul_f32_e32 v77, 0xbfb8aa3b, v77
	v_exp_f32_e32 v84, v78
	v_exp_f32_e32 v85, v79
	v_exp_f32_e32 v86, v80
	v_exp_f32_e32 v87, v81
	v_exp_f32_e32 v88, v74
	v_exp_f32_e32 v89, v75
	v_exp_f32_e32 v90, v76
	v_exp_f32_e32 v91, v77
	v_add_f32_e32 v84, 1.0, v84
	v_add_f32_e32 v85, 1.0, v85
	v_add_f32_e32 v86, 1.0, v86
	v_add_f32_e32 v87, 1.0, v87
	v_add_f32_e32 v88, 1.0, v88
	v_add_f32_e32 v89, 1.0, v89
	v_add_f32_e32 v90, 1.0, v90
	v_add_f32_e32 v91, 1.0, v91
	v_rcp_f32_e32 v84, v84
	v_rcp_f32_e32 v85, v85
	v_rcp_f32_e32 v86, v86
	v_rcp_f32_e32 v87, v87
	v_rcp_f32_e32 v88, v88
	v_rcp_f32_e32 v89, v89
	v_rcp_f32_e32 v90, v90
	v_rcp_f32_e32 v91, v91
	v_lshlrev_b32_e32 v74, 16, v92
	v_and_b32_e32 v75, 0xffff0000, v92
	v_lshlrev_b32_e32 v76, 16, v93
	v_and_b32_e32 v77, 0xffff0000, v93
	v_lshlrev_b32_e32 v78, 16, v94
	v_and_b32_e32 v79, 0xffff0000, v94
	v_lshlrev_b32_e32 v80, 16, v95
	v_and_b32_e32 v81, 0xffff0000, v95
	v_pk_mul_f32 v[92:93], v[84:85], v[74:75]
	v_pk_mul_f32 v[94:95], v[86:87], v[76:77]
	v_pk_mul_f32 v[88:89], v[88:89], v[78:79]
	v_pk_mul_f32 v[90:91], v[90:91], v[80:81]
	v_cvt_pk_bf16_f32 v74, v92, v93
	v_cvt_pk_bf16_f32 v75, v94, v95
	v_cvt_pk_bf16_f32 v76, v88, v89
	v_cvt_pk_bf16_f32 v77, v90, v91
	global_store_dwordx4 v[98:99], v[74:77], off offset:1024
	s_nop 0
	v_pk_mul_f32 v[92:93], v[92:93], v[92:93]
	v_pk_mul_f32 v[94:95], v[94:95], v[94:95]
	v_add_f32_e32 v92, v92, v93
	v_add_f32_e32 v92, v94, v92
	v_pk_mul_f32 v[88:89], v[88:89], v[88:89]
	v_add_f32_e32 v92, v95, v92
	v_add_f32_e32 v88, v88, v92
	v_pk_mul_f32 v[90:91], v[90:91], v[90:91]
	v_add_f32_e32 v88, v89, v88
	v_add_f32_e32 v88, v90, v88
	v_mov_b32_e32 v74, v192
	v_mov_b32_e32 v75, v193
	v_mov_b32_e32 v76, v194
	v_mov_b32_e32 v77, v195
	v_mov_b32_e32 v78, v196
	v_mov_b32_e32 v79, v197
	v_mov_b32_e32 v80, v198
	v_mov_b32_e32 v81, v199
	v_mov_b32_e32 v84, v214
	v_mov_b32_e32 v85, v215
	v_mov_b32_e32 v86, v216
	v_mov_b32_e32 v87, v217
	v_pk_add_f32 v[70:71], v[70:71], v[74:75]
	v_pk_add_f32 v[72:73], v[72:73], v[76:77]
	v_pk_add_f32 v[66:67], v[66:67], v[78:79]
	v_mul_f32_e32 v70, 0xbfb8aa3b, v70
	v_mul_f32_e32 v71, 0xbfb8aa3b, v71
	v_pk_add_f32 v[68:69], v[68:69], v[80:81]
	v_mul_f32_e32 v72, 0xbfb8aa3b, v72
	v_mul_f32_e32 v73, 0xbfb8aa3b, v73
	v_mul_f32_e32 v66, 0xbfb8aa3b, v66
	v_mul_f32_e32 v67, 0xbfb8aa3b, v67
	v_exp_f32_e32 v70, v70
	v_exp_f32_e32 v71, v71
	v_mul_f32_e32 v68, 0xbfb8aa3b, v68
	v_mul_f32_e32 v69, 0xbfb8aa3b, v69
	v_exp_f32_e32 v72, v72
	v_exp_f32_e32 v73, v73
	v_exp_f32_e32 v66, v66
	v_exp_f32_e32 v67, v67
	v_exp_f32_e32 v68, v68
	v_exp_f32_e32 v69, v69
	v_add_f32_e32 v70, 1.0, v70
	v_add_f32_e32 v71, 1.0, v71
	v_lshlrev_b32_e32 v74, 16, v84
	v_and_b32_e32 v75, 0xffff0000, v84
	v_lshlrev_b32_e32 v76, 16, v85
	v_and_b32_e32 v77, 0xffff0000, v85
	v_add_f32_e32 v72, 1.0, v72
	v_add_f32_e32 v73, 1.0, v73
	v_add_f32_e32 v84, 1.0, v66
	v_add_f32_e32 v85, 1.0, v67
	v_rcp_f32_e32 v66, v70
	v_rcp_f32_e32 v67, v71
	v_lshlrev_b32_e32 v78, 16, v86
	v_and_b32_e32 v79, 0xffff0000, v86
	v_lshlrev_b32_e32 v80, 16, v87
	v_and_b32_e32 v81, 0xffff0000, v87
	v_add_f32_e32 v86, 1.0, v68
	v_add_f32_e32 v87, 1.0, v69
	v_rcp_f32_e32 v68, v72
	v_rcp_f32_e32 v69, v73
	v_rcp_f32_e32 v70, v84
	v_rcp_f32_e32 v71, v85
	v_pk_mul_f32 v[66:67], v[66:67], v[74:75]
	v_pk_mul_f32 v[74:75], v[68:69], v[76:77]
	v_pk_mul_f32 v[68:69], v[66:67], v[66:67]
	v_add_f32_e32 v84, v91, v88
	v_rcp_f32_e32 v72, v86
	v_rcp_f32_e32 v73, v87
	v_add_f32_e32 v68, v68, v84
	v_pk_mul_f32 v[76:77], v[74:75], v[74:75]
	v_add_f32_e32 v68, v69, v68
	v_pk_mul_f32 v[70:71], v[70:71], v[78:79]
	v_add_f32_e32 v68, v76, v68
	v_pk_mul_f32 v[78:79], v[70:71], v[70:71]
	v_add_f32_e32 v68, v77, v68
	v_pk_mul_f32 v[72:73], v[72:73], v[80:81]
	v_add_f32_e32 v68, v78, v68
	v_pk_mul_f32 v[80:81], v[72:73], v[72:73]
	v_add_f32_e32 v68, v79, v68
	v_add_f32_e32 v68, v80, v68
	v_add_f32_e32 v69, v81, v68
	ds_bpermute_b32 v76, v122, v69
	v_cvt_pk_bf16_f32 v68, v66, v67
	v_cvt_pk_bf16_f32 v70, v70, v71
	v_cvt_pk_bf16_f32 v71, v72, v73
	s_waitcnt lgkmcnt(0)
	v_add_f32_e32 v66, v69, v76
	ds_bpermute_b32 v67, v116, v66
	v_cvt_pk_bf16_f32 v69, v74, v75
	global_store_dwordx4 v[98:99], v[68:71], off offset:1280
	s_and_saveexec_b64 s[22:23], s[4:5]
	s_cbranch_execz .LBB0_598
	s_add_u32 s26, s36, s92
	s_addc_u32 s27, s37, s93
	v_lshl_add_u64 v[68:69], v[82:83], 4, s[26:27]
	s_lshl_b32 s52, s38, 2
	v_lshl_add_u64 v[68:69], v[68:69], 0, s[52:53]
	s_waitcnt lgkmcnt(0)
	v_add_f32_e32 v66, v66, v67
	global_store_dword v[68:69], v66, off
; __device__ __forceinline__ unsigned cvt_pk_bf16(float lo, float hi) { const f32x2 v = {lo, hi}; return __builtin_bit_cast(unsigned, __builtin_convertvector(v, bf16x2_t)); }
; __device__ __forceinline__ float bf_lo(unsigned w) { return __uint_as_float(w << 16); }
; __device__ __forceinline__ float bf_hi(unsigned w) { return __uint_as_float(w & 0xffff0000u); }
; __device__ __forceinline__ float fast_sigmoid(float v) { return __builtin_amdgcn_rcpf(1.0f + __builtin_amdgcn_exp2f(-1.4426950408889634f * v)); }
; #define ssq2 ((float*)(WSPTR() + WS_SSQ2))
;     __device__ __forceinline__ void operator()(const f32x4 (&acc)[2][2][4][2], const Unit& u, int wr, int wc, int fr, int fq) const {
;     ...
;         for (int ai = 0; ai < 2; ++ai)
; #pragma unroll
;             for (int m = 0; m < 4; ++m) {
;                 const int row = row0 + ai * HALF + m * 16;
;                 float ss = 0.f;
; #pragma unroll
;                 for (int bj = 0; bj < 2; ++bj) {
;                     const int c0 = u.pn * BM + bj * HALF + wc * 32 + 8 * fq;
;                     const u32x4 zw = *(const u32x4*)(z + (size_t)row * 512 + c0);
;                     const f32x4 b0 = *(const f32x4*)(bglu + c0), b1 = *(const f32x4*)(bglu + c0 + 4);
;                     const f32x4 a0 = acc[ai][bj][m][0] + b0, a1 = acc[ai][bj][m][1] + b1;
;                     float o[8];
;                     o[0] = bf_lo(zw.x) * fast_sigmoid(a0[0]); o[1] = bf_hi(zw.x) * fast_sigmoid(a0[1]);
;                     o[2] = bf_lo(zw.y) * fast_sigmoid(a0[2]); o[3] = bf_hi(zw.y) * fast_sigmoid(a0[3]);
;                     o[4] = bf_lo(zw.z) * fast_sigmoid(a1[0]); o[5] = bf_hi(zw.z) * fast_sigmoid(a1[1]);
;                     o[6] = bf_lo(zw.w) * fast_sigmoid(a1[2]); o[7] = bf_hi(zw.w) * fast_sigmoid(a1[3]);
; #pragma unroll
;                     for (int j = 0; j < 8; ++j) ss += o[j] * o[j];
;                     u32x4 w; w.x = cvt_pk_bf16(o[0], o[1]); w.y = cvt_pk_bf16(o[2], o[3]); w.z = cvt_pk_bf16(o[4], o[5]); w.w = cvt_pk_bf16(o[6], o[7]);
;                     *(u32x4*)(s + (size_t)row * 1024 + 512 + c0) = w;
;                 }
;                 ss += __shfl_xor(ss, 16); ss += __shfl_xor(ss, 32); if (fq == 0) ssq2[((size_t)u.pn * 32768 + row) * 4 + wc] = ss;
;             }
.LBB0_598:
	s_or_b64 exec, exec, s[22:23]
	s_mov_b32 s100, 0x24000
	s_mov_b32 s101, 0
	v_lshl_add_u64 v[228:229], v[226:227], 0, s[100:101]
	global_load_dwordx4 v[210:213], v[228:229], off
	global_load_dwordx4 v[214:217], v[228:229], off offset:256
	s_waitcnt vmcnt(4)
	v_add_u32_e32 v66, 0x80, v144
	s_waitcnt lgkmcnt(0)
	v_ashrrev_i32_e32 v67, 31, v66
	v_lshlrev_b64 v[76:77], 10, v[66:67]
	v_lshl_add_u64 v[76:77], s[76:77], 0, v[76:77]
	v_lshl_add_u64 v[80:81], v[76:77], 0, v[142:143]
	v_lshlrev_b64 v[82:83], 11, v[66:67]
	v_lshl_add_u64 v[82:83], s[78:79], 0, v[82:83]
	v_lshl_add_u64 v[82:83], v[82:83], 0, v[142:143]
	v_mov_b32_e32 v68, v184
	v_mov_b32_e32 v69, v185
	v_mov_b32_e32 v70, v186
	v_mov_b32_e32 v71, v187
	v_mov_b32_e32 v72, v188
	v_mov_b32_e32 v73, v189
	v_mov_b32_e32 v74, v190
	v_mov_b32_e32 v75, v191
	v_mov_b32_e32 v76, v200
	v_mov_b32_e32 v77, v201
	v_mov_b32_e32 v78, v202
	v_mov_b32_e32 v79, v203
	v_pk_add_f32 v[64:65], v[64:65], v[70:71]
	v_pk_add_f32 v[62:63], v[62:63], v[68:69]
	v_pk_add_f32 v[60:61], v[60:61], v[74:75]
	v_pk_add_f32 v[58:59], v[58:59], v[72:73]
	v_mul_f32_e32 v62, 0xbfb8aa3b, v62
	v_mul_f32_e32 v63, 0xbfb8aa3b, v63
	v_mul_f32_e32 v64, 0xbfb8aa3b, v64
	v_mul_f32_e32 v65, 0xbfb8aa3b, v65
	v_mul_f32_e32 v58, 0xbfb8aa3b, v58
	v_mul_f32_e32 v59, 0xbfb8aa3b, v59
	v_mul_f32_e32 v60, 0xbfb8aa3b, v60
	v_mul_f32_e32 v61, 0xbfb8aa3b, v61
	v_exp_f32_e32 v68, v62
	v_exp_f32_e32 v69, v63
	v_exp_f32_e32 v70, v64
	v_exp_f32_e32 v71, v65
	v_exp_f32_e32 v72, v58
	v_exp_f32_e32 v73, v59
	v_exp_f32_e32 v74, v60
	v_exp_f32_e32 v75, v61
	v_add_f32_e32 v68, 1.0, v68
	v_add_f32_e32 v69, 1.0, v69
	v_add_f32_e32 v70, 1.0, v70
	v_add_f32_e32 v71, 1.0, v71
	v_add_f32_e32 v72, 1.0, v72
	v_add_f32_e32 v73, 1.0, v73
	v_add_f32_e32 v74, 1.0, v74
	v_add_f32_e32 v75, 1.0, v75
	v_rcp_f32_e32 v68, v68
	v_rcp_f32_e32 v69, v69
	v_rcp_f32_e32 v70, v70
	v_rcp_f32_e32 v71, v71
	v_rcp_f32_e32 v72, v72
	v_rcp_f32_e32 v73, v73
	v_rcp_f32_e32 v74, v74
	v_rcp_f32_e32 v75, v75
	v_lshlrev_b32_e32 v58, 16, v76
	v_and_b32_e32 v59, 0xffff0000, v76
	v_lshlrev_b32_e32 v60, 16, v77
	v_and_b32_e32 v61, 0xffff0000, v77
	v_lshlrev_b32_e32 v62, 16, v78
	v_and_b32_e32 v63, 0xffff0000, v78
	v_lshlrev_b32_e32 v64, 16, v79
	v_and_b32_e32 v65, 0xffff0000, v79
	v_pk_mul_f32 v[76:77], v[68:69], v[58:59]
	v_pk_mul_f32 v[78:79], v[70:71], v[60:61]
	v_pk_mul_f32 v[72:73], v[72:73], v[62:63]
	v_pk_mul_f32 v[74:75], v[74:75], v[64:65]
	v_cvt_pk_bf16_f32 v58, v76, v77
	v_cvt_pk_bf16_f32 v59, v78, v79
	v_cvt_pk_bf16_f32 v60, v72, v73
	v_cvt_pk_bf16_f32 v61, v74, v75
	global_store_dwordx4 v[82:83], v[58:61], off offset:1024
	s_nop 0
	v_pk_mul_f32 v[76:77], v[76:77], v[76:77]
	v_pk_mul_f32 v[78:79], v[78:79], v[78:79]
	v_add_f32_e32 v76, v76, v77
	v_add_f32_e32 v76, v78, v76
	v_pk_mul_f32 v[72:73], v[72:73], v[72:73]
	v_add_f32_e32 v76, v79, v76
	v_add_f32_e32 v72, v72, v76
	v_pk_mul_f32 v[74:75], v[74:75], v[74:75]
	v_add_f32_e32 v72, v73, v72
	v_add_f32_e32 v72, v74, v72
	v_mov_b32_e32 v58, v192
	v_mov_b32_e32 v59, v193
	v_mov_b32_e32 v60, v194
	v_mov_b32_e32 v61, v195
	v_mov_b32_e32 v62, v196
	v_mov_b32_e32 v63, v197
	v_mov_b32_e32 v64, v198
	v_mov_b32_e32 v65, v199
	v_mov_b32_e32 v68, v204
	v_mov_b32_e32 v69, v205
	v_mov_b32_e32 v70, v206
	v_mov_b32_e32 v71, v207
	v_pk_add_f32 v[54:55], v[54:55], v[58:59]
	v_pk_add_f32 v[56:57], v[56:57], v[60:61]
	v_pk_add_f32 v[50:51], v[50:51], v[62:63]
	v_mul_f32_e32 v54, 0xbfb8aa3b, v54
	v_mul_f32_e32 v55, 0xbfb8aa3b, v55
	v_pk_add_f32 v[52:53], v[52:53], v[64:65]
	v_mul_f32_e32 v56, 0xbfb8aa3b, v56
	v_mul_f32_e32 v57, 0xbfb8aa3b, v57
	v_mul_f32_e32 v50, 0xbfb8aa3b, v50
	v_mul_f32_e32 v51, 0xbfb8aa3b, v51
	v_exp_f32_e32 v54, v54
	v_exp_f32_e32 v55, v55
	v_mul_f32_e32 v52, 0xbfb8aa3b, v52
	v_mul_f32_e32 v53, 0xbfb8aa3b, v53
	v_exp_f32_e32 v56, v56
	v_exp_f32_e32 v57, v57
	v_exp_f32_e32 v50, v50
	v_exp_f32_e32 v51, v51
	v_exp_f32_e32 v52, v52
	v_exp_f32_e32 v53, v53
	v_add_f32_e32 v54, 1.0, v54
	v_add_f32_e32 v55, 1.0, v55
	v_lshlrev_b32_e32 v58, 16, v68
	v_and_b32_e32 v59, 0xffff0000, v68
	v_lshlrev_b32_e32 v60, 16, v69
	v_and_b32_e32 v61, 0xffff0000, v69
	v_add_f32_e32 v56, 1.0, v56
	v_add_f32_e32 v57, 1.0, v57
	v_add_f32_e32 v68, 1.0, v50
	v_add_f32_e32 v69, 1.0, v51
	v_rcp_f32_e32 v50, v54
	v_rcp_f32_e32 v51, v55
	v_lshlrev_b32_e32 v62, 16, v70
	v_and_b32_e32 v63, 0xffff0000, v70
	v_lshlrev_b32_e32 v64, 16, v71
	v_and_b32_e32 v65, 0xffff0000, v71
	v_add_f32_e32 v70, 1.0, v52
	v_add_f32_e32 v71, 1.0, v53
	v_rcp_f32_e32 v52, v56
	v_rcp_f32_e32 v53, v57
	v_rcp_f32_e32 v54, v68
	v_rcp_f32_e32 v55, v69
	v_pk_mul_f32 v[50:51], v[50:51], v[58:59]
	v_pk_mul_f32 v[58:59], v[52:53], v[60:61]
	v_pk_mul_f32 v[52:53], v[50:51], v[50:51]
	v_add_f32_e32 v68, v75, v72
	v_rcp_f32_e32 v56, v70
	v_rcp_f32_e32 v57, v71
	v_add_f32_e32 v52, v52, v68
	v_pk_mul_f32 v[60:61], v[58:59], v[58:59]
	v_add_f32_e32 v52, v53, v52
	v_pk_mul_f32 v[54:55], v[54:55], v[62:63]
	v_add_f32_e32 v52, v60, v52
	v_pk_mul_f32 v[62:63], v[54:55], v[54:55]
	v_add_f32_e32 v52, v61, v52
	v_pk_mul_f32 v[56:57], v[56:57], v[64:65]
	v_add_f32_e32 v52, v62, v52
	v_pk_mul_f32 v[64:65], v[56:57], v[56:57]
	v_add_f32_e32 v52, v63, v52
	v_add_f32_e32 v52, v64, v52
	v_add_f32_e32 v53, v65, v52
	ds_bpermute_b32 v60, v122, v53
	v_cvt_pk_bf16_f32 v52, v50, v51
	v_cvt_pk_bf16_f32 v54, v54, v55
	v_cvt_pk_bf16_f32 v55, v56, v57
	s_waitcnt lgkmcnt(0)
	v_add_f32_e32 v50, v53, v60
	ds_bpermute_b32 v51, v116, v50
	v_cvt_pk_bf16_f32 v53, v58, v59
	global_store_dwordx4 v[82:83], v[52:55], off offset:1280
	s_and_saveexec_b64 s[22:23], s[4:5]
	s_cbranch_execz .LBB0_600
	s_add_u32 s26, s36, s92
	s_addc_u32 s27, s37, s93
	v_lshl_add_u64 v[52:53], v[66:67], 4, s[26:27]
	s_lshl_b32 s52, s38, 2
	v_lshl_add_u64 v[52:53], v[52:53], 0, s[52:53]
	s_waitcnt lgkmcnt(0)
	v_add_f32_e32 v50, v50, v51
	global_store_dword v[52:53], v50, off
; __device__ __forceinline__ unsigned cvt_pk_bf16(float lo, float hi) { const f32x2 v = {lo, hi}; return __builtin_bit_cast(unsigned, __builtin_convertvector(v, bf16x2_t)); }
; __device__ __forceinline__ float bf_lo(unsigned w) { return __uint_as_float(w << 16); }
; __device__ __forceinline__ float bf_hi(unsigned w) { return __uint_as_float(w & 0xffff0000u); }
; __device__ __forceinline__ float fast_sigmoid(float v) { return __builtin_amdgcn_rcpf(1.0f + __builtin_amdgcn_exp2f(-1.4426950408889634f * v)); }
; #define ssq2 ((float*)(WSPTR() + WS_SSQ2))
;     __device__ __forceinline__ void operator()(const f32x4 (&acc)[2][2][4][2], const Unit& u, int wr, int wc, int fr, int fq) const {
;     ...
;         for (int ai = 0; ai < 2; ++ai)
; #pragma unroll
;             for (int m = 0; m < 4; ++m) {
;                 const int row = row0 + ai * HALF + m * 16;
;                 float ss = 0.f;
; #pragma unroll
;                 for (int bj = 0; bj < 2; ++bj) {
;                     const int c0 = u.pn * BM + bj * HALF + wc * 32 + 8 * fq;
;                     const u32x4 zw = *(const u32x4*)(z + (size_t)row * 512 + c0);
;                     const f32x4 b0 = *(const f32x4*)(bglu + c0), b1 = *(const f32x4*)(bglu + c0 + 4);
;                     const f32x4 a0 = acc[ai][bj][m][0] + b0, a1 = acc[ai][bj][m][1] + b1;
;                     float o[8];
;                     o[0] = bf_lo(zw.x) * fast_sigmoid(a0[0]); o[1] = bf_hi(zw.x) * fast_sigmoid(a0[1]);
;                     o[2] = bf_lo(zw.y) * fast_sigmoid(a0[2]); o[3] = bf_hi(zw.y) * fast_sigmoid(a0[3]);
;                     o[4] = bf_lo(zw.z) * fast_sigmoid(a1[0]); o[5] = bf_hi(zw.z) * fast_sigmoid(a1[1]);
;                     o[6] = bf_lo(zw.w) * fast_sigmoid(a1[2]); o[7] = bf_hi(zw.w) * fast_sigmoid(a1[3]);
; #pragma unroll
;                     for (int j = 0; j < 8; ++j) ss += o[j] * o[j];
;                     u32x4 w; w.x = cvt_pk_bf16(o[0], o[1]); w.y = cvt_pk_bf16(o[2], o[3]); w.z = cvt_pk_bf16(o[4], o[5]); w.w = cvt_pk_bf16(o[6], o[7]);
;                     *(u32x4*)(s + (size_t)row * 1024 + 512 + c0) = w;
;                 }
;                 ss += __shfl_xor(ss, 16); ss += __shfl_xor(ss, 32); if (fq == 0) ssq2[((size_t)u.pn * 32768 + row) * 4 + wc] = ss;
;             }
.LBB0_600:
	s_or_b64 exec, exec, s[22:23]
	s_mov_b32 s100, 0x28000
	s_mov_b32 s101, 0
	v_lshl_add_u64 v[228:229], v[226:227], 0, s[100:101]
	global_load_dwordx4 v[200:203], v[228:229], off
	global_load_dwordx4 v[204:207], v[228:229], off offset:256
	s_waitcnt vmcnt(4)
	v_add_u32_e32 v50, 0x90, v144
	s_waitcnt lgkmcnt(0)
	v_ashrrev_i32_e32 v51, 31, v50
	v_lshlrev_b64 v[60:61], 10, v[50:51]
	v_lshl_add_u64 v[60:61], s[76:77], 0, v[60:61]
	v_lshl_add_u64 v[64:65], v[60:61], 0, v[142:143]
	v_lshlrev_b64 v[66:67], 11, v[50:51]
	v_lshl_add_u64 v[66:67], s[78:79], 0, v[66:67]
	v_lshl_add_u64 v[66:67], v[66:67], 0, v[142:143]
	v_mov_b32_e32 v52, v184
	v_mov_b32_e32 v53, v185
	v_mov_b32_e32 v54, v186
	v_mov_b32_e32 v55, v187
	v_mov_b32_e32 v56, v188
	v_mov_b32_e32 v57, v189
	v_mov_b32_e32 v58, v190
	v_mov_b32_e32 v59, v191
	v_mov_b32_e32 v60, v210
	v_mov_b32_e32 v61, v211
	v_mov_b32_e32 v62, v212
	v_mov_b32_e32 v63, v213
	v_pk_add_f32 v[48:49], v[48:49], v[54:55]
	v_pk_add_f32 v[46:47], v[46:47], v[52:53]
	v_pk_add_f32 v[44:45], v[44:45], v[58:59]
	v_pk_add_f32 v[42:43], v[42:43], v[56:57]
	v_mul_f32_e32 v46, 0xbfb8aa3b, v46
	v_mul_f32_e32 v47, 0xbfb8aa3b, v47
	v_mul_f32_e32 v48, 0xbfb8aa3b, v48
	v_mul_f32_e32 v49, 0xbfb8aa3b, v49
	v_mul_f32_e32 v42, 0xbfb8aa3b, v42
	v_mul_f32_e32 v43, 0xbfb8aa3b, v43
	v_mul_f32_e32 v44, 0xbfb8aa3b, v44
	v_mul_f32_e32 v45, 0xbfb8aa3b, v45
	v_exp_f32_e32 v52, v46
	v_exp_f32_e32 v53, v47
	v_exp_f32_e32 v54, v48
	v_exp_f32_e32 v55, v49
	v_exp_f32_e32 v56, v42
	v_exp_f32_e32 v57, v43
	v_exp_f32_e32 v58, v44
	v_exp_f32_e32 v59, v45
	v_add_f32_e32 v52, 1.0, v52
	v_add_f32_e32 v53, 1.0, v53
	v_add_f32_e32 v54, 1.0, v54
	v_add_f32_e32 v55, 1.0, v55
	v_add_f32_e32 v56, 1.0, v56
	v_add_f32_e32 v57, 1.0, v57
	v_add_f32_e32 v58, 1.0, v58
	v_add_f32_e32 v59, 1.0, v59
	v_rcp_f32_e32 v52, v52
	v_rcp_f32_e32 v53, v53
	v_rcp_f32_e32 v54, v54
	v_rcp_f32_e32 v55, v55
	v_rcp_f32_e32 v56, v56
	v_rcp_f32_e32 v57, v57
	v_rcp_f32_e32 v58, v58
	v_rcp_f32_e32 v59, v59
	v_lshlrev_b32_e32 v42, 16, v60
	v_and_b32_e32 v43, 0xffff0000, v60
	v_lshlrev_b32_e32 v44, 16, v61
	v_and_b32_e32 v45, 0xffff0000, v61
	v_lshlrev_b32_e32 v46, 16, v62
	v_and_b32_e32 v47, 0xffff0000, v62
	v_lshlrev_b32_e32 v48, 16, v63
	v_and_b32_e32 v49, 0xffff0000, v63
	v_pk_mul_f32 v[60:61], v[52:53], v[42:43]
	v_pk_mul_f32 v[62:63], v[54:55], v[44:45]
	v_pk_mul_f32 v[56:57], v[56:57], v[46:47]
	v_pk_mul_f32 v[58:59], v[58:59], v[48:49]
	v_cvt_pk_bf16_f32 v42, v60, v61
	v_cvt_pk_bf16_f32 v43, v62, v63
	v_cvt_pk_bf16_f32 v44, v56, v57
	v_cvt_pk_bf16_f32 v45, v58, v59
	global_store_dwordx4 v[66:67], v[42:45], off offset:1024
	s_nop 0
	v_pk_mul_f32 v[60:61], v[60:61], v[60:61]
	v_pk_mul_f32 v[62:63], v[62:63], v[62:63]
	v_add_f32_e32 v60, v60, v61
	v_add_f32_e32 v60, v62, v60
	v_pk_mul_f32 v[56:57], v[56:57], v[56:57]
	v_add_f32_e32 v60, v63, v60
	v_add_f32_e32 v56, v56, v60
	v_pk_mul_f32 v[58:59], v[58:59], v[58:59]
	v_add_f32_e32 v56, v57, v56
	v_add_f32_e32 v56, v58, v56
	v_mov_b32_e32 v42, v192
	v_mov_b32_e32 v43, v193
	v_mov_b32_e32 v44, v194
	v_mov_b32_e32 v45, v195
	v_mov_b32_e32 v46, v196
	v_mov_b32_e32 v47, v197
	v_mov_b32_e32 v48, v198
	v_mov_b32_e32 v49, v199
	v_mov_b32_e32 v52, v214
	v_mov_b32_e32 v53, v215
	v_mov_b32_e32 v54, v216
	v_mov_b32_e32 v55, v217
	v_pk_add_f32 v[38:39], v[38:39], v[42:43]
	v_pk_add_f32 v[40:41], v[40:41], v[44:45]
	v_pk_add_f32 v[34:35], v[34:35], v[46:47]
	v_mul_f32_e32 v38, 0xbfb8aa3b, v38
	v_mul_f32_e32 v39, 0xbfb8aa3b, v39
	v_pk_add_f32 v[36:37], v[36:37], v[48:49]
	v_mul_f32_e32 v40, 0xbfb8aa3b, v40
	v_mul_f32_e32 v41, 0xbfb8aa3b, v41
	v_mul_f32_e32 v34, 0xbfb8aa3b, v34
	v_mul_f32_e32 v35, 0xbfb8aa3b, v35
	v_exp_f32_e32 v38, v38
	v_exp_f32_e32 v39, v39
	v_mul_f32_e32 v36, 0xbfb8aa3b, v36
	v_mul_f32_e32 v37, 0xbfb8aa3b, v37
	v_exp_f32_e32 v40, v40
	v_exp_f32_e32 v41, v41
	v_exp_f32_e32 v34, v34
	v_exp_f32_e32 v35, v35
	v_exp_f32_e32 v36, v36
	v_exp_f32_e32 v37, v37
	v_add_f32_e32 v38, 1.0, v38
	v_add_f32_e32 v39, 1.0, v39
	v_lshlrev_b32_e32 v42, 16, v52
	v_and_b32_e32 v43, 0xffff0000, v52
	v_lshlrev_b32_e32 v44, 16, v53
	v_and_b32_e32 v45, 0xffff0000, v53
	v_add_f32_e32 v40, 1.0, v40
	v_add_f32_e32 v41, 1.0, v41
	v_add_f32_e32 v52, 1.0, v34
	v_add_f32_e32 v53, 1.0, v35
	v_rcp_f32_e32 v34, v38
	v_rcp_f32_e32 v35, v39
	v_lshlrev_b32_e32 v46, 16, v54
	v_and_b32_e32 v47, 0xffff0000, v54
	v_lshlrev_b32_e32 v48, 16, v55
	v_and_b32_e32 v49, 0xffff0000, v55
	v_add_f32_e32 v54, 1.0, v36
	v_add_f32_e32 v55, 1.0, v37
	v_rcp_f32_e32 v36, v40
	v_rcp_f32_e32 v37, v41
	v_rcp_f32_e32 v38, v52
	v_rcp_f32_e32 v39, v53
	v_pk_mul_f32 v[34:35], v[34:35], v[42:43]
	v_pk_mul_f32 v[42:43], v[36:37], v[44:45]
	v_pk_mul_f32 v[36:37], v[34:35], v[34:35]
	v_add_f32_e32 v52, v59, v56
	v_rcp_f32_e32 v40, v54
	v_rcp_f32_e32 v41, v55
	v_add_f32_e32 v36, v36, v52
	v_pk_mul_f32 v[44:45], v[42:43], v[42:43]
	v_add_f32_e32 v36, v37, v36
	v_pk_mul_f32 v[38:39], v[38:39], v[46:47]
	v_add_f32_e32 v36, v44, v36
	v_pk_mul_f32 v[46:47], v[38:39], v[38:39]
	v_add_f32_e32 v36, v45, v36
	v_pk_mul_f32 v[40:41], v[40:41], v[48:49]
	v_add_f32_e32 v36, v46, v36
	v_pk_mul_f32 v[48:49], v[40:41], v[40:41]
	v_add_f32_e32 v36, v47, v36
	v_add_f32_e32 v36, v48, v36
	v_add_f32_e32 v37, v49, v36
	ds_bpermute_b32 v44, v122, v37
	v_cvt_pk_bf16_f32 v36, v34, v35
	v_cvt_pk_bf16_f32 v38, v38, v39
	v_cvt_pk_bf16_f32 v39, v40, v41
	s_waitcnt lgkmcnt(0)
	v_add_f32_e32 v34, v37, v44
	ds_bpermute_b32 v35, v116, v34
	v_cvt_pk_bf16_f32 v37, v42, v43
	global_store_dwordx4 v[66:67], v[36:39], off offset:1280
	s_and_saveexec_b64 s[22:23], s[4:5]
	s_cbranch_execz .LBB0_602
	s_add_u32 s26, s36, s92
	s_addc_u32 s27, s37, s93
	v_lshl_add_u64 v[36:37], v[50:51], 4, s[26:27]
	s_lshl_b32 s52, s38, 2
	v_lshl_add_u64 v[36:37], v[36:37], 0, s[52:53]
	s_waitcnt lgkmcnt(0)
	v_add_f32_e32 v34, v34, v35
	global_store_dword v[36:37], v34, off
; __device__ __forceinline__ unsigned cvt_pk_bf16(float lo, float hi) { const f32x2 v = {lo, hi}; return __builtin_bit_cast(unsigned, __builtin_convertvector(v, bf16x2_t)); }
; __device__ __forceinline__ float bf_lo(unsigned w) { return __uint_as_float(w << 16); }
; __device__ __forceinline__ float bf_hi(unsigned w) { return __uint_as_float(w & 0xffff0000u); }
; __device__ __forceinline__ float fast_sigmoid(float v) { return __builtin_amdgcn_rcpf(1.0f + __builtin_amdgcn_exp2f(-1.4426950408889634f * v)); }
; #define ssq2 ((float*)(WSPTR() + WS_SSQ2))
;     __device__ __forceinline__ void operator()(const f32x4 (&acc)[2][2][4][2], const Unit& u, int wr, int wc, int fr, int fq) const {
;     ...
;         for (int ai = 0; ai < 2; ++ai)
; #pragma unroll
;             for (int m = 0; m < 4; ++m) {
;                 const int row = row0 + ai * HALF + m * 16;
;                 float ss = 0.f;
; #pragma unroll
;                 for (int bj = 0; bj < 2; ++bj) {
;                     const int c0 = u.pn * BM + bj * HALF + wc * 32 + 8 * fq;
;                     const u32x4 zw = *(const u32x4*)(z + (size_t)row * 512 + c0);
;                     const f32x4 b0 = *(const f32x4*)(bglu + c0), b1 = *(const f32x4*)(bglu + c0 + 4);
;                     const f32x4 a0 = acc[ai][bj][m][0] + b0, a1 = acc[ai][bj][m][1] + b1;
;                     float o[8];
;                     o[0] = bf_lo(zw.x) * fast_sigmoid(a0[0]); o[1] = bf_hi(zw.x) * fast_sigmoid(a0[1]);
;                     o[2] = bf_lo(zw.y) * fast_sigmoid(a0[2]); o[3] = bf_hi(zw.y) * fast_sigmoid(a0[3]);
;                     o[4] = bf_lo(zw.z) * fast_sigmoid(a1[0]); o[5] = bf_hi(zw.z) * fast_sigmoid(a1[1]);
;                     o[6] = bf_lo(zw.w) * fast_sigmoid(a1[2]); o[7] = bf_hi(zw.w) * fast_sigmoid(a1[3]);
; #pragma unroll
;                     for (int j = 0; j < 8; ++j) ss += o[j] * o[j];
;                     u32x4 w; w.x = cvt_pk_bf16(o[0], o[1]); w.y = cvt_pk_bf16(o[2], o[3]); w.z = cvt_pk_bf16(o[4], o[5]); w.w = cvt_pk_bf16(o[6], o[7]);
;                     *(u32x4*)(s + (size_t)row * 1024 + 512 + c0) = w;
;                 }
;                 ss += __shfl_xor(ss, 16); ss += __shfl_xor(ss, 32); if (fq == 0) ssq2[((size_t)u.pn * 32768 + row) * 4 + wc] = ss;
;             }
.LBB0_602:
	s_or_b64 exec, exec, s[22:23]
	s_mov_b32 s100, 0x2c000
	s_mov_b32 s101, 0
	v_lshl_add_u64 v[228:229], v[226:227], 0, s[100:101]
	global_load_dwordx4 v[210:213], v[228:229], off
	global_load_dwordx4 v[214:217], v[228:229], off offset:256
	s_waitcnt vmcnt(4)
	v_add_u32_e32 v34, 0xa0, v144
	s_waitcnt lgkmcnt(0)
	v_ashrrev_i32_e32 v35, 31, v34
	v_lshlrev_b64 v[44:45], 10, v[34:35]
	v_lshl_add_u64 v[44:45], s[76:77], 0, v[44:45]
	v_lshl_add_u64 v[48:49], v[44:45], 0, v[142:143]
	v_lshlrev_b64 v[50:51], 11, v[34:35]
	v_lshl_add_u64 v[50:51], s[78:79], 0, v[50:51]
	v_lshl_add_u64 v[50:51], v[50:51], 0, v[142:143]
	v_mov_b32_e32 v36, v184
	v_mov_b32_e32 v37, v185
	v_mov_b32_e32 v38, v186
	v_mov_b32_e32 v39, v187
	v_mov_b32_e32 v40, v188
	v_mov_b32_e32 v41, v189
	v_mov_b32_e32 v42, v190
	v_mov_b32_e32 v43, v191
	v_mov_b32_e32 v44, v200
	v_mov_b32_e32 v45, v201
	v_mov_b32_e32 v46, v202
	v_mov_b32_e32 v47, v203
	v_pk_add_f32 v[32:33], v[32:33], v[38:39]
	v_pk_add_f32 v[30:31], v[30:31], v[36:37]
	v_pk_add_f32 v[28:29], v[28:29], v[42:43]
	v_pk_add_f32 v[26:27], v[26:27], v[40:41]
	v_mul_f32_e32 v30, 0xbfb8aa3b, v30
	v_mul_f32_e32 v31, 0xbfb8aa3b, v31
	v_mul_f32_e32 v32, 0xbfb8aa3b, v32
	v_mul_f32_e32 v33, 0xbfb8aa3b, v33
	v_mul_f32_e32 v26, 0xbfb8aa3b, v26
	v_mul_f32_e32 v27, 0xbfb8aa3b, v27
	v_mul_f32_e32 v28, 0xbfb8aa3b, v28
	v_mul_f32_e32 v29, 0xbfb8aa3b, v29
	v_exp_f32_e32 v36, v30
	v_exp_f32_e32 v37, v31
	v_exp_f32_e32 v38, v32
	v_exp_f32_e32 v39, v33
	v_exp_f32_e32 v40, v26
	v_exp_f32_e32 v41, v27
	v_exp_f32_e32 v42, v28
	v_exp_f32_e32 v43, v29
	v_add_f32_e32 v36, 1.0, v36
	v_add_f32_e32 v37, 1.0, v37
	v_add_f32_e32 v38, 1.0, v38
	v_add_f32_e32 v39, 1.0, v39
	v_add_f32_e32 v40, 1.0, v40
	v_add_f32_e32 v41, 1.0, v41
	v_add_f32_e32 v42, 1.0, v42
	v_add_f32_e32 v43, 1.0, v43
	v_rcp_f32_e32 v36, v36
	v_rcp_f32_e32 v37, v37
	v_rcp_f32_e32 v38, v38
	v_rcp_f32_e32 v39, v39
	v_rcp_f32_e32 v40, v40
	v_rcp_f32_e32 v41, v41
	v_rcp_f32_e32 v42, v42
	v_rcp_f32_e32 v43, v43
	v_lshlrev_b32_e32 v26, 16, v44
	v_and_b32_e32 v27, 0xffff0000, v44
	v_lshlrev_b32_e32 v28, 16, v45
	v_and_b32_e32 v29, 0xffff0000, v45
	v_lshlrev_b32_e32 v30, 16, v46
	v_and_b32_e32 v31, 0xffff0000, v46
	v_lshlrev_b32_e32 v32, 16, v47
	v_and_b32_e32 v33, 0xffff0000, v47
	v_pk_mul_f32 v[44:45], v[36:37], v[26:27]
	v_pk_mul_f32 v[46:47], v[38:39], v[28:29]
	v_pk_mul_f32 v[40:41], v[40:41], v[30:31]
	v_pk_mul_f32 v[42:43], v[42:43], v[32:33]
	v_cvt_pk_bf16_f32 v26, v44, v45
	v_cvt_pk_bf16_f32 v27, v46, v47
	v_cvt_pk_bf16_f32 v28, v40, v41
	v_cvt_pk_bf16_f32 v29, v42, v43
	global_store_dwordx4 v[50:51], v[26:29], off offset:1024
	s_nop 0
	v_pk_mul_f32 v[44:45], v[44:45], v[44:45]
	v_pk_mul_f32 v[46:47], v[46:47], v[46:47]
	v_add_f32_e32 v44, v44, v45
	v_add_f32_e32 v44, v46, v44
	v_pk_mul_f32 v[40:41], v[40:41], v[40:41]
	v_add_f32_e32 v44, v47, v44
	v_add_f32_e32 v40, v40, v44
	v_pk_mul_f32 v[42:43], v[42:43], v[42:43]
	v_add_f32_e32 v40, v41, v40
	v_add_f32_e32 v40, v42, v40
	v_mov_b32_e32 v26, v192
	v_mov_b32_e32 v27, v193
	v_mov_b32_e32 v28, v194
	v_mov_b32_e32 v29, v195
	v_mov_b32_e32 v30, v196
	v_mov_b32_e32 v31, v197
	v_mov_b32_e32 v32, v198
	v_mov_b32_e32 v33, v199
	v_mov_b32_e32 v36, v204
	v_mov_b32_e32 v37, v205
	v_mov_b32_e32 v38, v206
	v_mov_b32_e32 v39, v207
	v_pk_add_f32 v[22:23], v[22:23], v[26:27]
	v_pk_add_f32 v[24:25], v[24:25], v[28:29]
	v_pk_add_f32 v[18:19], v[18:19], v[30:31]
	v_mul_f32_e32 v22, 0xbfb8aa3b, v22
	v_mul_f32_e32 v23, 0xbfb8aa3b, v23
	v_pk_add_f32 v[20:21], v[20:21], v[32:33]
	v_mul_f32_e32 v24, 0xbfb8aa3b, v24
	v_mul_f32_e32 v25, 0xbfb8aa3b, v25
	v_mul_f32_e32 v18, 0xbfb8aa3b, v18
	v_mul_f32_e32 v19, 0xbfb8aa3b, v19
	v_exp_f32_e32 v22, v22
	v_exp_f32_e32 v23, v23
	v_mul_f32_e32 v20, 0xbfb8aa3b, v20
	v_mul_f32_e32 v21, 0xbfb8aa3b, v21
	v_exp_f32_e32 v24, v24
	v_exp_f32_e32 v25, v25
	v_exp_f32_e32 v18, v18
	v_exp_f32_e32 v19, v19
	v_exp_f32_e32 v20, v20
	v_exp_f32_e32 v21, v21
	v_add_f32_e32 v22, 1.0, v22
	v_add_f32_e32 v23, 1.0, v23
	v_lshlrev_b32_e32 v26, 16, v36
	v_and_b32_e32 v27, 0xffff0000, v36
	v_lshlrev_b32_e32 v28, 16, v37
	v_and_b32_e32 v29, 0xffff0000, v37
	v_add_f32_e32 v24, 1.0, v24
	v_add_f32_e32 v25, 1.0, v25
	v_add_f32_e32 v36, 1.0, v18
	v_add_f32_e32 v37, 1.0, v19
	v_rcp_f32_e32 v18, v22
	v_rcp_f32_e32 v19, v23
	v_lshlrev_b32_e32 v30, 16, v38
	v_and_b32_e32 v31, 0xffff0000, v38
	v_lshlrev_b32_e32 v32, 16, v39
	v_and_b32_e32 v33, 0xffff0000, v39
	v_add_f32_e32 v38, 1.0, v20
	v_add_f32_e32 v39, 1.0, v21
	v_rcp_f32_e32 v20, v24
	v_rcp_f32_e32 v21, v25
	v_rcp_f32_e32 v22, v36
	v_rcp_f32_e32 v23, v37
	v_pk_mul_f32 v[18:19], v[18:19], v[26:27]
	v_pk_mul_f32 v[26:27], v[20:21], v[28:29]
	v_pk_mul_f32 v[20:21], v[18:19], v[18:19]
	v_add_f32_e32 v36, v43, v40
	v_rcp_f32_e32 v24, v38
	v_rcp_f32_e32 v25, v39
	v_add_f32_e32 v20, v20, v36
	v_pk_mul_f32 v[28:29], v[26:27], v[26:27]
	v_add_f32_e32 v20, v21, v20
	v_pk_mul_f32 v[22:23], v[22:23], v[30:31]
	v_add_f32_e32 v20, v28, v20
	v_pk_mul_f32 v[30:31], v[22:23], v[22:23]
	v_add_f32_e32 v20, v29, v20
	v_pk_mul_f32 v[24:25], v[24:25], v[32:33]
	v_add_f32_e32 v20, v30, v20
	v_pk_mul_f32 v[32:33], v[24:25], v[24:25]
	v_add_f32_e32 v20, v31, v20
	v_add_f32_e32 v20, v32, v20
	v_add_f32_e32 v21, v33, v20
	ds_bpermute_b32 v28, v122, v21
	v_cvt_pk_bf16_f32 v20, v18, v19
	v_cvt_pk_bf16_f32 v22, v22, v23
	v_cvt_pk_bf16_f32 v23, v24, v25
	s_waitcnt lgkmcnt(0)
	v_add_f32_e32 v18, v21, v28
	ds_bpermute_b32 v19, v116, v18
	v_cvt_pk_bf16_f32 v21, v26, v27
	global_store_dwordx4 v[50:51], v[20:23], off offset:1280
	s_and_saveexec_b64 s[22:23], s[4:5]
	s_cbranch_execz .LBB0_604
	s_add_u32 s26, s36, s92
	s_addc_u32 s27, s37, s93
	v_lshl_add_u64 v[20:21], v[34:35], 4, s[26:27]
	s_lshl_b32 s52, s38, 2
	v_lshl_add_u64 v[20:21], v[20:21], 0, s[52:53]
	s_waitcnt lgkmcnt(0)
	v_add_f32_e32 v18, v18, v19
	global_store_dword v[20:21], v18, off
; __device__ __forceinline__ unsigned cvt_pk_bf16(float lo, float hi) { const f32x2 v = {lo, hi}; return __builtin_bit_cast(unsigned, __builtin_convertvector(v, bf16x2_t)); }
; __device__ __forceinline__ float bf_lo(unsigned w) { return __uint_as_float(w << 16); }
; __device__ __forceinline__ float bf_hi(unsigned w) { return __uint_as_float(w & 0xffff0000u); }
; __device__ __forceinline__ float fast_sigmoid(float v) { return __builtin_amdgcn_rcpf(1.0f + __builtin_amdgcn_exp2f(-1.4426950408889634f * v)); }
; #define ssq2 ((float*)(WSPTR() + WS_SSQ2))
;     __device__ __forceinline__ void operator()(const f32x4 (&acc)[2][2][4][2], const Unit& u, int wr, int wc, int fr, int fq) const {
;     ...
;         for (int ai = 0; ai < 2; ++ai)
; #pragma unroll
;             for (int m = 0; m < 4; ++m) {
;                 const int row = row0 + ai * HALF + m * 16;
;                 float ss = 0.f;
; #pragma unroll
;                 for (int bj = 0; bj < 2; ++bj) {
;                     const int c0 = u.pn * BM + bj * HALF + wc * 32 + 8 * fq;
;                     const u32x4 zw = *(const u32x4*)(z + (size_t)row * 512 + c0);
;                     const f32x4 b0 = *(const f32x4*)(bglu + c0), b1 = *(const f32x4*)(bglu + c0 + 4);
;                     const f32x4 a0 = acc[ai][bj][m][0] + b0, a1 = acc[ai][bj][m][1] + b1;
;                     float o[8];
;                     o[0] = bf_lo(zw.x) * fast_sigmoid(a0[0]); o[1] = bf_hi(zw.x) * fast_sigmoid(a0[1]);
;                     o[2] = bf_lo(zw.y) * fast_sigmoid(a0[2]); o[3] = bf_hi(zw.y) * fast_sigmoid(a0[3]);
;                     o[4] = bf_lo(zw.z) * fast_sigmoid(a1[0]); o[5] = bf_hi(zw.z) * fast_sigmoid(a1[1]);
;                     o[6] = bf_lo(zw.w) * fast_sigmoid(a1[2]); o[7] = bf_hi(zw.w) * fast_sigmoid(a1[3]);
; #pragma unroll
;                     for (int j = 0; j < 8; ++j) ss += o[j] * o[j];
;                     u32x4 w; w.x = cvt_pk_bf16(o[0], o[1]); w.y = cvt_pk_bf16(o[2], o[3]); w.z = cvt_pk_bf16(o[4], o[5]); w.w = cvt_pk_bf16(o[6], o[7]);
;                     *(u32x4*)(s + (size_t)row * 1024 + 512 + c0) = w;
;                 }
;                 ss += __shfl_xor(ss, 16); ss += __shfl_xor(ss, 32); if (fq == 0) ssq2[((size_t)u.pn * 32768 + row) * 4 + wc] = ss;
;             }
.LBB0_604:
	s_or_b64 exec, exec, s[22:23]
	s_waitcnt vmcnt(2)
	v_add_u32_e32 v18, 0xb0, v144
	s_waitcnt lgkmcnt(0)
	v_ashrrev_i32_e32 v19, 31, v18
	v_lshlrev_b64 v[28:29], 10, v[18:19]
	v_lshl_add_u64 v[28:29], s[76:77], 0, v[28:29]
	v_lshl_add_u64 v[32:33], v[28:29], 0, v[142:143]
	v_lshlrev_b64 v[34:35], 11, v[18:19]
	v_lshl_add_u64 v[34:35], s[78:79], 0, v[34:35]
	v_lshl_add_u64 v[34:35], v[34:35], 0, v[142:143]
	v_mov_b32_e32 v20, v184
	v_mov_b32_e32 v21, v185
	v_mov_b32_e32 v22, v186
	v_mov_b32_e32 v23, v187
	v_mov_b32_e32 v24, v188
	v_mov_b32_e32 v25, v189
	v_mov_b32_e32 v26, v190
	v_mov_b32_e32 v27, v191
	v_mov_b32_e32 v28, v210
	v_mov_b32_e32 v29, v211
	v_mov_b32_e32 v30, v212
	v_mov_b32_e32 v31, v213
	v_pk_add_f32 v[16:17], v[16:17], v[22:23]
	v_pk_add_f32 v[14:15], v[14:15], v[20:21]
	v_pk_add_f32 v[12:13], v[12:13], v[26:27]
	v_pk_add_f32 v[10:11], v[10:11], v[24:25]
	v_mul_f32_e32 v14, 0xbfb8aa3b, v14
	v_mul_f32_e32 v15, 0xbfb8aa3b, v15
	v_mul_f32_e32 v16, 0xbfb8aa3b, v16
	v_mul_f32_e32 v17, 0xbfb8aa3b, v17
	v_mul_f32_e32 v10, 0xbfb8aa3b, v10
	v_mul_f32_e32 v11, 0xbfb8aa3b, v11
	v_mul_f32_e32 v12, 0xbfb8aa3b, v12
	v_mul_f32_e32 v13, 0xbfb8aa3b, v13
	v_exp_f32_e32 v20, v14
	v_exp_f32_e32 v21, v15
	v_exp_f32_e32 v22, v16
	v_exp_f32_e32 v23, v17
	v_exp_f32_e32 v24, v10
	v_exp_f32_e32 v25, v11
	v_exp_f32_e32 v26, v12
	v_exp_f32_e32 v27, v13
	v_add_f32_e32 v20, 1.0, v20
	v_add_f32_e32 v21, 1.0, v21
	v_add_f32_e32 v22, 1.0, v22
	v_add_f32_e32 v23, 1.0, v23
	v_add_f32_e32 v24, 1.0, v24
	v_add_f32_e32 v25, 1.0, v25
	v_add_f32_e32 v26, 1.0, v26
	v_add_f32_e32 v27, 1.0, v27
	v_rcp_f32_e32 v20, v20
	v_rcp_f32_e32 v21, v21
	v_rcp_f32_e32 v22, v22
	v_rcp_f32_e32 v23, v23
	v_rcp_f32_e32 v24, v24
	v_rcp_f32_e32 v25, v25
	v_rcp_f32_e32 v26, v26
	v_rcp_f32_e32 v27, v27
	v_lshlrev_b32_e32 v10, 16, v28
	v_and_b32_e32 v11, 0xffff0000, v28
	v_lshlrev_b32_e32 v12, 16, v29
	v_and_b32_e32 v13, 0xffff0000, v29
	v_lshlrev_b32_e32 v14, 16, v30
	v_and_b32_e32 v15, 0xffff0000, v30
	v_lshlrev_b32_e32 v16, 16, v31
	v_and_b32_e32 v17, 0xffff0000, v31
	v_pk_mul_f32 v[28:29], v[20:21], v[10:11]
	v_pk_mul_f32 v[30:31], v[22:23], v[12:13]
	v_pk_mul_f32 v[24:25], v[24:25], v[14:15]
	v_pk_mul_f32 v[26:27], v[26:27], v[16:17]
	v_cvt_pk_bf16_f32 v10, v28, v29
	v_cvt_pk_bf16_f32 v11, v30, v31
	v_cvt_pk_bf16_f32 v12, v24, v25
	v_cvt_pk_bf16_f32 v13, v26, v27
	global_store_dwordx4 v[34:35], v[10:13], off offset:1024
	s_nop 0
	v_pk_mul_f32 v[28:29], v[28:29], v[28:29]
	v_pk_mul_f32 v[30:31], v[30:31], v[30:31]
	v_add_f32_e32 v28, v28, v29
	v_add_f32_e32 v28, v30, v28
	v_pk_mul_f32 v[24:25], v[24:25], v[24:25]
	v_add_f32_e32 v28, v31, v28
	v_add_f32_e32 v24, v24, v28
	v_pk_mul_f32 v[26:27], v[26:27], v[26:27]
	v_add_f32_e32 v24, v25, v24
	v_add_f32_e32 v24, v26, v24
	v_mov_b32_e32 v10, v192
	v_mov_b32_e32 v11, v193
	v_mov_b32_e32 v12, v194
	v_mov_b32_e32 v13, v195
	v_mov_b32_e32 v14, v196
	v_mov_b32_e32 v15, v197
	v_mov_b32_e32 v16, v198
	v_mov_b32_e32 v17, v199
	v_mov_b32_e32 v20, v214
	v_mov_b32_e32 v21, v215
	v_mov_b32_e32 v22, v216
	v_mov_b32_e32 v23, v217
	v_pk_add_f32 v[6:7], v[6:7], v[10:11]
	v_pk_add_f32 v[8:9], v[8:9], v[12:13]
	v_pk_add_f32 v[2:3], v[2:3], v[14:15]
	v_mul_f32_e32 v6, 0xbfb8aa3b, v6
	v_mul_f32_e32 v7, 0xbfb8aa3b, v7
	v_pk_add_f32 v[4:5], v[4:5], v[16:17]
	v_mul_f32_e32 v8, 0xbfb8aa3b, v8
	v_mul_f32_e32 v9, 0xbfb8aa3b, v9
	v_mul_f32_e32 v2, 0xbfb8aa3b, v2
	v_mul_f32_e32 v3, 0xbfb8aa3b, v3
	v_exp_f32_e32 v6, v6
	v_exp_f32_e32 v7, v7
	v_mul_f32_e32 v4, 0xbfb8aa3b, v4
	v_mul_f32_e32 v5, 0xbfb8aa3b, v5
	v_exp_f32_e32 v8, v8
	v_exp_f32_e32 v9, v9
	v_exp_f32_e32 v2, v2
	v_exp_f32_e32 v3, v3
	v_exp_f32_e32 v4, v4
	v_exp_f32_e32 v5, v5
	v_add_f32_e32 v6, 1.0, v6
	v_add_f32_e32 v7, 1.0, v7
	v_lshlrev_b32_e32 v10, 16, v20
	v_and_b32_e32 v11, 0xffff0000, v20
	v_lshlrev_b32_e32 v12, 16, v21
	v_and_b32_e32 v13, 0xffff0000, v21
	v_add_f32_e32 v8, 1.0, v8
	v_add_f32_e32 v9, 1.0, v9
	v_add_f32_e32 v20, 1.0, v2
	v_add_f32_e32 v21, 1.0, v3
	v_rcp_f32_e32 v2, v6
	v_rcp_f32_e32 v3, v7
	v_lshlrev_b32_e32 v14, 16, v22
	v_and_b32_e32 v15, 0xffff0000, v22
	v_lshlrev_b32_e32 v16, 16, v23
	v_and_b32_e32 v17, 0xffff0000, v23
	v_add_f32_e32 v22, 1.0, v4
	v_add_f32_e32 v23, 1.0, v5
	v_rcp_f32_e32 v4, v8
	v_rcp_f32_e32 v5, v9
	v_rcp_f32_e32 v6, v20
	v_rcp_f32_e32 v7, v21
	v_pk_mul_f32 v[2:3], v[2:3], v[10:11]
	v_pk_mul_f32 v[10:11], v[4:5], v[12:13]
	v_pk_mul_f32 v[4:5], v[2:3], v[2:3]
	v_add_f32_e32 v20, v27, v24
	v_rcp_f32_e32 v8, v22
	v_rcp_f32_e32 v9, v23
	v_add_f32_e32 v4, v4, v20
	v_pk_mul_f32 v[12:13], v[10:11], v[10:11]
	v_add_f32_e32 v4, v5, v4
	v_pk_mul_f32 v[6:7], v[6:7], v[14:15]
	v_add_f32_e32 v4, v12, v4
	v_pk_mul_f32 v[14:15], v[6:7], v[6:7]
	v_add_f32_e32 v4, v13, v4
	v_pk_mul_f32 v[8:9], v[8:9], v[16:17]
	v_add_f32_e32 v4, v14, v4
	v_pk_mul_f32 v[16:17], v[8:9], v[8:9]
	v_add_f32_e32 v4, v15, v4
	v_add_f32_e32 v4, v16, v4
	v_add_f32_e32 v5, v17, v4
	ds_bpermute_b32 v12, v122, v5
	v_cvt_pk_bf16_f32 v4, v2, v3
	v_cvt_pk_bf16_f32 v6, v6, v7
	v_cvt_pk_bf16_f32 v7, v8, v9
	s_waitcnt lgkmcnt(0)
	v_add_f32_e32 v2, v5, v12
	ds_bpermute_b32 v3, v116, v2
	v_cvt_pk_bf16_f32 v5, v10, v11
	global_store_dwordx4 v[34:35], v[4:7], off offset:1280
	s_and_saveexec_b64 s[22:23], s[4:5]
	s_cbranch_execz .LBB0_606
	s_add_u32 s26, s36, s92
	s_addc_u32 s27, s37, s93
	v_lshl_add_u64 v[4:5], v[18:19], 4, s[26:27]
	s_lshl_b32 s52, s38, 2
	v_lshl_add_u64 v[4:5], v[4:5], 0, s[52:53]
	s_waitcnt lgkmcnt(0)
	v_add_f32_e32 v2, v2, v3
	global_store_dword v[4:5], v2, off
